# ff2 split-K of sample rows 4->16 slices (128 mini units), split units first, sample_combine and EpiRes loads batched
# speedup vs baseline: 1.0292x; 1.0292x over previous
;     __host__ __device__ bool next(int i, Unit& u) const {
;         const long L = (long)i * G + c; if (L >= nwg + nsp) return false;
;         if (L >= nwg) { const int Ls = (int)L - nwg, t = Ls / S, sl = Ls % S; u.pk = mark ? -2 : sl; u.pn = pn0 + t % nNs; u.pm = pm0 + t / nNs; u.kofs = sl * nts * BK; u.nt = nts; return true; }
;         int wgid = (int)L; { const int q = nwg / NXCD, r = nwg % NXCD, xcd = wgid % NXCD, off = wgid / NXCD; wgid = (xcd < r ? xcd * (q + 1) : r * (q + 1) + (xcd - r) * q) + off; }
;         const int nig = WGM * nN, gid = wgid / nig, fm = gid * WGM, gsz = (nM - fm) < WGM ? (nM - fm) : WGM;
;         u.pm = fm + ((wgid % nig) % gsz); u.pn = (wgid % nig) / gsz; u.pk = -1; u.kofs = 0; u.nt = nt; return true;
.LBB0_534:
	s_andn2_b64 vcc, exec, s[2:3]
	s_cbranch_vccnz .LBB0_646
	s_add_u32 s2, s0, s92
	s_mov_b32 s10, s76
	s_addc_u32 s3, s1, s93
	s_waitcnt lgkmcnt(0)
	s_load_dwordx2 s[34:35], s[0:1], 0x98
	s_load_dwordx2 s[14:15], s[2:3], 0x0
	s_load_dwordx2 s[22:23], s[0:1], 0x90
	v_mov_b32_e32 v8, v173
	s_cmp_lt_u32 s10, 32
	s_cselect_b32 s24, 0x100, 0
	s_cmp_lt_u32 s10, 0x100
	s_cselect_b32 s88, 0, 0x100
	s_cmp_lt_u32 s10, 0x120
	s_cselect_b32 s88, s88, 0
	s_add_u32 s10, s10, s24
	s_sub_u32 s10, s10, s88
	s_cmpk_lt_i32 s10, 0x120
	s_cselect_b64 s[26:27], -1, 0
	s_cmpk_gt_i32 s10, 0x11f
	v_readfirstlane_b32 s36, v8
	s_cbranch_scc1 .LBB0_544
	s_cmpk_lt_i32 s10, 0x100
	s_mov_b64 s[28:29], -1
	s_cbranch_scc1 .LBB0_538
	s_bfe_u32 s11, s10, 0x60002
	s_and_b32 s4, s10, 3
	v_sub_co_u32_e64 v0, s[2:3], s11, 4
	s_and_b64 s[2:3], s[2:3], exec
	v_readfirstlane_b32 s2, v0
	s_cselect_b32 s88, s11, s2
	s_cmp_gt_u32 s11, 3
	s_cselect_b32 s24, 0x41, 64
	s_lshl_b32 s2, s4, 8
	s_mov_b64 s[28:29], 0

;     __host__ __device__ bool next(int i, Unit& u) const {
;         const long L = (long)i * G + c; if (L >= nwg + nsp) return false;
;         if (L >= nwg) { const int Ls = (int)L - nwg, t = Ls / S, sl = Ls % S; u.pk = mark ? -2 : sl; u.pn = pn0 + t % nNs; u.pm = pm0 + t / nNs; u.kofs = sl * nts * BK; u.nt = nts; return true; }
;         int wgid = (int)L; { const int q = nwg / NXCD, r = nwg % NXCD, xcd = wgid % NXCD, off = wgid / NXCD; wgid = (xcd < r ? xcd * (q + 1) : r * (q + 1) + (xcd - r) * q) + off; }
;         const int nig = WGM * nN, gid = wgid / nig, fm = gid * WGM, gsz = (nM - fm) < WGM ? (nM - fm) : WGM;
;         u.pm = fm + ((wgid % nig) % gsz); u.pn = (wgid % nig) / gsz; u.pk = -1; u.kofs = 0; u.nt = nt; return true;
.LBB0_550:
	s_mov_b32 s10, s76
	s_add_i32 s65, s65, 1
	s_mul_i32 s37, s65, s48
	s_mul_hi_u32 s40, s65, s33
	s_add_i32 s37, s40, s37
	s_mul_i32 s40, s65, s33
	s_add_u32 s40, s40, s10
	s_addc_u32 s41, s37, s66
	v_cmp_gt_i64_e32 vcc, s[40:41], v[160:161]
	v_cmp_lt_i64_e64 s[42:43], s[40:41], v[158:159]
	s_cbranch_vccnz .LBB0_559
	s_cmp_lt_u32 s40, 32
	s_cselect_b32 s36, 0x100, 0
	s_cmp_lt_u32 s40, 0x100
	s_cselect_b32 s37, 0, 0x100
	s_cmp_lt_u32 s40, 0x120
	s_cselect_b32 s37, s37, 0
	s_add_u32 s40, s40, s36
	s_sub_u32 s40, s40, s37
	v_cmp_lt_i64_e32 vcc, s[40:41], v[162:163]
	s_mov_b64 s[50:51], -1
	s_and_b64 vcc, exec, vcc
	s_cbranch_vccnz .LBB0_553
	s_add_i32 s36, s40, 0xffffff00
	s_ashr_i32 s37, s36, 31
	s_lshr_b32 s41, s37, 30
	s_add_i32 s41, s36, s41
	s_ashr_i32 s44, s41, 2
	s_and_b32 s41, s41, -4
	s_sub_i32 s67, s36, s41
	s_lshr_b32 s41, s44, 30
	s_lshr_b32 s37, s37, 28
	s_add_i32 s41, s44, s41
	s_add_i32 s36, s36, s37
	s_and_b32 s41, s41, -4
	s_ashr_i32 s36, s36, 4
	s_sub_i32 s44, s44, s41
	s_add_i32 s46, s36, 64
	s_lshl_b32 s36, s67, 8
	s_mov_b64 s[50:51], 0

; __device__ __forceinline__ unsigned pk2(float lo, float hi) { f32x2 v = {lo, hi}; bf16x2_t b = __builtin_convertvector(v, bf16x2_t); return __builtin_bit_cast(unsigned, b); }
;     __device__ __forceinline__ void operator()(const f32x4 (&acc)[2][2][4][2], const Unit& u, int wr, int wc, int fr, int fq) const {
;     ...
; #pragma unroll
;         for (int ai = 0; ai < 2; ++ai)
; #pragma unroll
;             for (int m = 0; m < 4; ++m) { const int row = u.pm * BM + ai * HALF + wr * 64 + m * 16 + fr; const size_t off = (size_t)row * DM + col0; float ss = 0.f;
; #pragma unroll
;                 for (int bj = 0; bj < 2; ++bj)
; #pragma unroll
;                     for (int n = 0; n < 2; ++n) { float* p = X + off + bj * HALF + n * 16; const f32x4 x = *(const f32x4*)(Xin + off + bj * HALF + n * 16) + acc[ai][bj][m][n]; *(f32x4*)p = x;
;                         ss += (x[0] * x[0] + x[1] * x[1]) + (x[2] * x[2] + x[3] * x[3]);
;                         if (XB) { u32x2 w; w.x = pk2(x[0], x[1]); w.y = pk2(x[2], x[3]); *(u32x2*)(XB + off + bj * HALF + n * 16) = w; } }
;                 if (rss_out) { ss += __shfl_xor(ss, 16); ss += __shfl_xor(ss, 32); if (fq == 0) atomicAdd(rss_out + row, ss); } }
.LBB0_570:
	s_lshl_b32 s37, s24, 8
	v_add_u32_e32 v136, s37, v142
	v_lshl_add_u32 v156, v136, 10, v134
	v_lshlrev_b32_e32 v156, 2, v156
	global_load_dwordx4 v[192:195], v156, s[14:15]
	global_load_dwordx4 v[200:203], v156, s[14:15] offset:64
	global_load_dwordx4 v[204:207], v156, s[14:15] offset:512
	global_load_dwordx4 v[208:211], v156, s[14:15] offset:576
	v_add_u32_e32 v157, 0x10000, v156
	global_load_dwordx4 v[212:215], v157, s[14:15]
	global_load_dwordx4 v[216:219], v157, s[14:15] offset:64
	global_load_dwordx4 v[220:223], v157, s[14:15] offset:512
	global_load_dwordx4 v[228:231], v157, s[14:15] offset:576
	v_add_u32_e32 v157, 0x20000, v156
	global_load_dwordx4 v[232:235], v157, s[14:15]
	global_load_dwordx4 v[236:239], v157, s[14:15] offset:64
	global_load_dwordx4 v[240:243], v157, s[14:15] offset:512
	global_load_dwordx4 v[244:247], v157, s[14:15] offset:576
	v_xor_b32_e32 v169, 16, v191
	v_xor_b32_e32 v170, 32, v191
	v_lshlrev_b32_e32 v169, 2, v169
	v_lshlrev_b32_e32 v170, 2, v170
	s_waitcnt vmcnt(8)
	v_lshrrev_b32_e32 v174, 1, v156
	v_pk_add_f32 v[192:193], v[124:125], v[192:193]
	v_pk_add_f32 v[194:195], v[126:127], v[194:195]
	global_store_dwordx4 v156, v[192:195], s[22:23]
	v_mul_f32_e32 v137, v193, v193
	v_fmac_f32_e32 v137, v192, v192
	v_mul_f32_e32 v172, v195, v195
	v_fmac_f32_e32 v172, v194, v194
	v_cvt_pk_bf16_f32 v138, v192, v193
	v_cvt_pk_bf16_f32 v139, v194, v195
	global_store_dwordx2 v174, v[138:139], s[28:29]
	v_add_f32_e32 v137, v137, v172
	v_pk_add_f32 v[200:201], v[120:121], v[200:201]
	v_pk_add_f32 v[202:203], v[122:123], v[202:203]
	global_store_dwordx4 v156, v[200:203], s[22:23] offset:64
	v_mul_f32_e32 v171, v201, v201
	v_fmac_f32_e32 v171, v200, v200
	v_mul_f32_e32 v172, v203, v203
	v_fmac_f32_e32 v172, v202, v202
	v_cvt_pk_bf16_f32 v140, v200, v201
	v_cvt_pk_bf16_f32 v141, v202, v203
	global_store_dwordx2 v174, v[140:141], s[28:29] offset:32
	v_add_f32_e32 v171, v171, v172
	v_add_f32_e32 v137, v137, v171
	v_pk_add_f32 v[204:205], v[108:109], v[204:205]
	v_pk_add_f32 v[206:207], v[110:111], v[206:207]
	global_store_dwordx4 v156, v[204:207], s[22:23] offset:512
	v_mul_f32_e32 v171, v205, v205
	v_fmac_f32_e32 v171, v204, v204
	v_mul_f32_e32 v172, v207, v207
	v_fmac_f32_e32 v172, v206, v206
	v_cvt_pk_bf16_f32 v138, v204, v205
	v_cvt_pk_bf16_f32 v139, v206, v207
	global_store_dwordx2 v174, v[138:139], s[28:29] offset:256
	v_add_f32_e32 v171, v171, v172
	v_add_f32_e32 v137, v137, v171
	v_pk_add_f32 v[208:209], v[100:101], v[208:209]
	v_pk_add_f32 v[210:211], v[102:103], v[210:211]
	global_store_dwordx4 v156, v[208:211], s[22:23] offset:576
	v_mul_f32_e32 v171, v209, v209
	v_fmac_f32_e32 v171, v208, v208
	v_mul_f32_e32 v172, v211, v211
	v_fmac_f32_e32 v172, v210, v210
	v_cvt_pk_bf16_f32 v140, v208, v209
	v_cvt_pk_bf16_f32 v141, v210, v211
	global_store_dwordx2 v174, v[140:141], s[28:29] offset:288
	v_add_f32_e32 v171, v171, v172
	v_add_f32_e32 v137, v137, v171
	ds_bpermute_b32 v180, v169, v137
	v_add_u32_e32 v181, 0x0, v136
	v_lshlrev_b32_e32 v181, 2, v181
	s_waitcnt lgkmcnt(0)
	v_add_f32_e32 v137, v137, v180
	ds_bpermute_b32 v180, v170, v137
	s_waitcnt lgkmcnt(0)
	v_add_f32_e32 v137, v137, v180
	s_and_saveexec_b64 s[2:3], s[38:39]
	global_atomic_add_f32 v181, v137, s[30:31]
	s_or_b64 exec, exec, s[2:3]
	v_add_u32_e32 v157, 0x30000, v156
	global_load_dwordx4 v[192:195], v157, s[14:15]
	global_load_dwordx4 v[200:203], v157, s[14:15] offset:64
	global_load_dwordx4 v[204:207], v157, s[14:15] offset:512
	global_load_dwordx4 v[208:211], v157, s[14:15] offset:576
	s_waitcnt vmcnt(16)
	v_add_u32_e32 v157, 0x10000, v156
	v_lshrrev_b32_e32 v174, 1, v157
	v_pk_add_f32 v[212:213], v[116:117], v[212:213]
	v_pk_add_f32 v[214:215], v[118:119], v[214:215]
	global_store_dwordx4 v157, v[212:215], s[22:23]
	v_mul_f32_e32 v137, v213, v213
	v_fmac_f32_e32 v137, v212, v212
	v_mul_f32_e32 v172, v215, v215
	v_fmac_f32_e32 v172, v214, v214
	v_cvt_pk_bf16_f32 v138, v212, v213
	v_cvt_pk_bf16_f32 v139, v214, v215
	global_store_dwordx2 v174, v[138:139], s[28:29]
	v_add_f32_e32 v137, v137, v172
	v_pk_add_f32 v[216:217], v[112:113], v[216:217]
	v_pk_add_f32 v[218:219], v[114:115], v[218:219]
	global_store_dwordx4 v157, v[216:219], s[22:23] offset:64
	v_mul_f32_e32 v171, v217, v217
	v_fmac_f32_e32 v171, v216, v216
	v_mul_f32_e32 v172, v219, v219
	v_fmac_f32_e32 v172, v218, v218
	v_cvt_pk_bf16_f32 v140, v216, v217
	v_cvt_pk_bf16_f32 v141, v218, v219
	global_store_dwordx2 v174, v[140:141], s[28:29] offset:32
	v_add_f32_e32 v171, v171, v172
	v_add_f32_e32 v137, v137, v171
	v_pk_add_f32 v[220:221], v[92:93], v[220:221]
	v_pk_add_f32 v[222:223], v[94:95], v[222:223]
	global_store_dwordx4 v157, v[220:223], s[22:23] offset:512
	v_mul_f32_e32 v171, v221, v221
	v_fmac_f32_e32 v171, v220, v220
	v_mul_f32_e32 v172, v223, v223
	v_fmac_f32_e32 v172, v222, v222
	v_cvt_pk_bf16_f32 v138, v220, v221
	v_cvt_pk_bf16_f32 v139, v222, v223
	global_store_dwordx2 v174, v[138:139], s[28:29] offset:256
	v_add_f32_e32 v171, v171, v172
	v_add_f32_e32 v137, v137, v171
	v_pk_add_f32 v[228:229], v[84:85], v[228:229]
	v_pk_add_f32 v[230:231], v[86:87], v[230:231]
	global_store_dwordx4 v157, v[228:231], s[22:23] offset:576
	v_mul_f32_e32 v171, v229, v229
	v_fmac_f32_e32 v171, v228, v228
	v_mul_f32_e32 v172, v231, v231
	v_fmac_f32_e32 v172, v230, v230
	v_cvt_pk_bf16_f32 v140, v228, v229
	v_cvt_pk_bf16_f32 v141, v230, v231
	global_store_dwordx2 v174, v[140:141], s[28:29] offset:288
	v_add_f32_e32 v171, v171, v172
	v_add_f32_e32 v137, v137, v171
	ds_bpermute_b32 v180, v169, v137
	v_add_u32_e32 v181, 0x10, v136
	v_lshlrev_b32_e32 v181, 2, v181
	s_waitcnt lgkmcnt(0)
; __device__ __forceinline__ unsigned pk2(float lo, float hi) { f32x2 v = {lo, hi}; bf16x2_t b = __builtin_convertvector(v, bf16x2_t); return __builtin_bit_cast(unsigned, b); }
;     __device__ __forceinline__ void operator()(const f32x4 (&acc)[2][2][4][2], const Unit& u, int wr, int wc, int fr, int fq) const {
;     ...
; #pragma unroll
;         for (int ai = 0; ai < 2; ++ai)
; #pragma unroll
;             for (int m = 0; m < 4; ++m) { const int row = u.pm * BM + ai * HALF + wr * 64 + m * 16 + fr; const size_t off = (size_t)row * DM + col0; float ss = 0.f;
; #pragma unroll
;                 for (int bj = 0; bj < 2; ++bj)
; #pragma unroll
;                     for (int n = 0; n < 2; ++n) { float* p = X + off + bj * HALF + n * 16; const f32x4 x = *(const f32x4*)(Xin + off + bj * HALF + n * 16) + acc[ai][bj][m][n]; *(f32x4*)p = x;
;                         ss += (x[0] * x[0] + x[1] * x[1]) + (x[2] * x[2] + x[3] * x[3]);
;                         if (XB) { u32x2 w; w.x = pk2(x[0], x[1]); w.y = pk2(x[2], x[3]); *(u32x2*)(XB + off + bj * HALF + n * 16) = w; } }
;                 if (rss_out) { ss += __shfl_xor(ss, 16); ss += __shfl_xor(ss, 32); if (fq == 0) atomicAdd(rss_out + row, ss); } }
	v_add_f32_e32 v137, v137, v180
	ds_bpermute_b32 v180, v170, v137
	s_waitcnt lgkmcnt(0)
	v_add_f32_e32 v137, v137, v180
	s_and_saveexec_b64 s[2:3], s[38:39]
	global_atomic_add_f32 v181, v137, s[30:31]
	s_or_b64 exec, exec, s[2:3]
	v_add_u32_e32 v157, 0x80000, v156
	global_load_dwordx4 v[212:215], v157, s[14:15]
	global_load_dwordx4 v[216:219], v157, s[14:15] offset:64
	global_load_dwordx4 v[220:223], v157, s[14:15] offset:512
	global_load_dwordx4 v[228:231], v157, s[14:15] offset:576
	s_waitcnt vmcnt(24)
	v_add_u32_e32 v157, 0x20000, v156
	v_lshrrev_b32_e32 v174, 1, v157
	v_pk_add_f32 v[232:233], v[104:105], v[232:233]
	v_pk_add_f32 v[234:235], v[106:107], v[234:235]
	global_store_dwordx4 v157, v[232:235], s[22:23]
	v_mul_f32_e32 v137, v233, v233
	v_fmac_f32_e32 v137, v232, v232
	v_mul_f32_e32 v172, v235, v235
	v_fmac_f32_e32 v172, v234, v234
	v_cvt_pk_bf16_f32 v138, v232, v233
	v_cvt_pk_bf16_f32 v139, v234, v235
	global_store_dwordx2 v174, v[138:139], s[28:29]
	v_add_f32_e32 v137, v137, v172
	v_pk_add_f32 v[236:237], v[96:97], v[236:237]
	v_pk_add_f32 v[238:239], v[98:99], v[238:239]
	global_store_dwordx4 v157, v[236:239], s[22:23] offset:64
	v_mul_f32_e32 v171, v237, v237
	v_fmac_f32_e32 v171, v236, v236
	v_mul_f32_e32 v172, v239, v239
	v_fmac_f32_e32 v172, v238, v238
	v_cvt_pk_bf16_f32 v140, v236, v237
	v_cvt_pk_bf16_f32 v141, v238, v239
	global_store_dwordx2 v174, v[140:141], s[28:29] offset:32
	v_add_f32_e32 v171, v171, v172
	v_add_f32_e32 v137, v137, v171
	v_pk_add_f32 v[240:241], v[76:77], v[240:241]
	v_pk_add_f32 v[242:243], v[78:79], v[242:243]
	global_store_dwordx4 v157, v[240:243], s[22:23] offset:512
	v_mul_f32_e32 v171, v241, v241
	v_fmac_f32_e32 v171, v240, v240
	v_mul_f32_e32 v172, v243, v243
	v_fmac_f32_e32 v172, v242, v242
	v_cvt_pk_bf16_f32 v138, v240, v241
	v_cvt_pk_bf16_f32 v139, v242, v243
	global_store_dwordx2 v174, v[138:139], s[28:29] offset:256
	v_add_f32_e32 v171, v171, v172
	v_add_f32_e32 v137, v137, v171
	v_pk_add_f32 v[244:245], v[72:73], v[244:245]
	v_pk_add_f32 v[246:247], v[74:75], v[246:247]
	global_store_dwordx4 v157, v[244:247], s[22:23] offset:576
	v_mul_f32_e32 v171, v245, v245
	v_fmac_f32_e32 v171, v244, v244
	v_mul_f32_e32 v172, v247, v247
	v_fmac_f32_e32 v172, v246, v246
	v_cvt_pk_bf16_f32 v140, v244, v245
	v_cvt_pk_bf16_f32 v141, v246, v247
	global_store_dwordx2 v174, v[140:141], s[28:29] offset:288
	v_add_f32_e32 v171, v171, v172
	v_add_f32_e32 v137, v137, v171
	ds_bpermute_b32 v180, v169, v137
	v_add_u32_e32 v181, 0x20, v136
	v_lshlrev_b32_e32 v181, 2, v181
	s_waitcnt lgkmcnt(0)
	v_add_f32_e32 v137, v137, v180
	ds_bpermute_b32 v180, v170, v137
	s_waitcnt lgkmcnt(0)
	v_add_f32_e32 v137, v137, v180
	s_and_saveexec_b64 s[2:3], s[38:39]
	global_atomic_add_f32 v181, v137, s[30:31]
	s_or_b64 exec, exec, s[2:3]
	v_add_u32_e32 v157, 0x90000, v156
	global_load_dwordx4 v[232:235], v157, s[14:15]
	global_load_dwordx4 v[236:239], v157, s[14:15] offset:64
	global_load_dwordx4 v[240:243], v157, s[14:15] offset:512
	global_load_dwordx4 v[244:247], v157, s[14:15] offset:576
	s_waitcnt vmcnt(24)
	v_add_u32_e32 v157, 0x30000, v156
	v_lshrrev_b32_e32 v174, 1, v157
	v_pk_add_f32 v[192:193], v[88:89], v[192:193]
	v_pk_add_f32 v[194:195], v[90:91], v[194:195]
	global_store_dwordx4 v157, v[192:195], s[22:23]
	v_mul_f32_e32 v137, v193, v193
	v_fmac_f32_e32 v137, v192, v192
	v_mul_f32_e32 v172, v195, v195
	v_fmac_f32_e32 v172, v194, v194
	v_cvt_pk_bf16_f32 v138, v192, v193
	v_cvt_pk_bf16_f32 v139, v194, v195
	global_store_dwordx2 v174, v[138:139], s[28:29]
	v_add_f32_e32 v137, v137, v172
	v_pk_add_f32 v[200:201], v[80:81], v[200:201]
	v_pk_add_f32 v[202:203], v[82:83], v[202:203]
	global_store_dwordx4 v157, v[200:203], s[22:23] offset:64
	v_mul_f32_e32 v171, v201, v201
	v_fmac_f32_e32 v171, v200, v200
	v_mul_f32_e32 v172, v203, v203
	v_fmac_f32_e32 v172, v202, v202
	v_cvt_pk_bf16_f32 v140, v200, v201
	v_cvt_pk_bf16_f32 v141, v202, v203
	global_store_dwordx2 v174, v[140:141], s[28:29] offset:32
	v_add_f32_e32 v171, v171, v172
	v_add_f32_e32 v137, v137, v171
	v_pk_add_f32 v[204:205], v[68:69], v[204:205]
	v_pk_add_f32 v[206:207], v[70:71], v[206:207]
	global_store_dwordx4 v157, v[204:207], s[22:23] offset:512
	v_mul_f32_e32 v171, v205, v205
	v_fmac_f32_e32 v171, v204, v204
	v_mul_f32_e32 v172, v207, v207
	v_fmac_f32_e32 v172, v206, v206
	v_cvt_pk_bf16_f32 v138, v204, v205
	v_cvt_pk_bf16_f32 v139, v206, v207
	global_store_dwordx2 v174, v[138:139], s[28:29] offset:256
	v_add_f32_e32 v171, v171, v172
	v_add_f32_e32 v137, v137, v171
	v_pk_add_f32 v[208:209], v[64:65], v[208:209]
	v_pk_add_f32 v[210:211], v[66:67], v[210:211]
	global_store_dwordx4 v157, v[208:211], s[22:23] offset:576
	v_mul_f32_e32 v171, v209, v209
	v_fmac_f32_e32 v171, v208, v208
	v_mul_f32_e32 v172, v211, v211
	v_fmac_f32_e32 v172, v210, v210
	v_cvt_pk_bf16_f32 v140, v208, v209
	v_cvt_pk_bf16_f32 v141, v210, v211
	global_store_dwordx2 v174, v[140:141], s[28:29] offset:288
	v_add_f32_e32 v171, v171, v172
	v_add_f32_e32 v137, v137, v171
	ds_bpermute_b32 v180, v169, v137
	v_add_u32_e32 v181, 0x30, v136
	v_lshlrev_b32_e32 v181, 2, v181
	s_waitcnt lgkmcnt(0)
	v_add_f32_e32 v137, v137, v180
	ds_bpermute_b32 v180, v170, v137
	s_waitcnt lgkmcnt(0)
	v_add_f32_e32 v137, v137, v180
	s_and_saveexec_b64 s[2:3], s[38:39]
	global_atomic_add_f32 v181, v137, s[30:31]
	s_or_b64 exec, exec, s[2:3]
	v_add_u32_e32 v157, 0xa0000, v156
	global_load_dwordx4 v[192:195], v157, s[14:15]
	global_load_dwordx4 v[200:203], v157, s[14:15] offset:64
	global_load_dwordx4 v[204:207], v157, s[14:15] offset:512
	global_load_dwordx4 v[208:211], v157, s[14:15] offset:576
	s_waitcnt vmcnt(24)
; __device__ __forceinline__ unsigned pk2(float lo, float hi) { f32x2 v = {lo, hi}; bf16x2_t b = __builtin_convertvector(v, bf16x2_t); return __builtin_bit_cast(unsigned, b); }
;     __device__ __forceinline__ void operator()(const f32x4 (&acc)[2][2][4][2], const Unit& u, int wr, int wc, int fr, int fq) const {
;     ...
; #pragma unroll
;         for (int ai = 0; ai < 2; ++ai)
; #pragma unroll
;             for (int m = 0; m < 4; ++m) { const int row = u.pm * BM + ai * HALF + wr * 64 + m * 16 + fr; const size_t off = (size_t)row * DM + col0; float ss = 0.f;
; #pragma unroll
;                 for (int bj = 0; bj < 2; ++bj)
; #pragma unroll
;                     for (int n = 0; n < 2; ++n) { float* p = X + off + bj * HALF + n * 16; const f32x4 x = *(const f32x4*)(Xin + off + bj * HALF + n * 16) + acc[ai][bj][m][n]; *(f32x4*)p = x;
;                         ss += (x[0] * x[0] + x[1] * x[1]) + (x[2] * x[2] + x[3] * x[3]);
;                         if (XB) { u32x2 w; w.x = pk2(x[0], x[1]); w.y = pk2(x[2], x[3]); *(u32x2*)(XB + off + bj * HALF + n * 16) = w; } }
;                 if (rss_out) { ss += __shfl_xor(ss, 16); ss += __shfl_xor(ss, 32); if (fq == 0) atomicAdd(rss_out + row, ss); } }
	v_add_u32_e32 v157, 0x80000, v156
	v_lshrrev_b32_e32 v174, 1, v157
	v_pk_add_f32 v[212:213], v[60:61], v[212:213]
	v_pk_add_f32 v[214:215], v[62:63], v[214:215]
	global_store_dwordx4 v157, v[212:215], s[22:23]
	v_mul_f32_e32 v137, v213, v213
	v_fmac_f32_e32 v137, v212, v212
	v_mul_f32_e32 v172, v215, v215
	v_fmac_f32_e32 v172, v214, v214
	v_cvt_pk_bf16_f32 v138, v212, v213
	v_cvt_pk_bf16_f32 v139, v214, v215
	global_store_dwordx2 v174, v[138:139], s[28:29]
	v_add_f32_e32 v137, v137, v172
	v_pk_add_f32 v[216:217], v[56:57], v[216:217]
	v_pk_add_f32 v[218:219], v[58:59], v[218:219]
	global_store_dwordx4 v157, v[216:219], s[22:23] offset:64
	v_mul_f32_e32 v171, v217, v217
	v_fmac_f32_e32 v171, v216, v216
	v_mul_f32_e32 v172, v219, v219
	v_fmac_f32_e32 v172, v218, v218
	v_cvt_pk_bf16_f32 v140, v216, v217
	v_cvt_pk_bf16_f32 v141, v218, v219
	global_store_dwordx2 v174, v[140:141], s[28:29] offset:32
	v_add_f32_e32 v171, v171, v172
	v_add_f32_e32 v137, v137, v171
	v_pk_add_f32 v[220:221], v[44:45], v[220:221]
	v_pk_add_f32 v[222:223], v[46:47], v[222:223]
	global_store_dwordx4 v157, v[220:223], s[22:23] offset:512
	v_mul_f32_e32 v171, v221, v221
	v_fmac_f32_e32 v171, v220, v220
	v_mul_f32_e32 v172, v223, v223
	v_fmac_f32_e32 v172, v222, v222
	v_cvt_pk_bf16_f32 v138, v220, v221
	v_cvt_pk_bf16_f32 v139, v222, v223
	global_store_dwordx2 v174, v[138:139], s[28:29] offset:256
	v_add_f32_e32 v171, v171, v172
	v_add_f32_e32 v137, v137, v171
	v_pk_add_f32 v[228:229], v[36:37], v[228:229]
	v_pk_add_f32 v[230:231], v[38:39], v[230:231]
	global_store_dwordx4 v157, v[228:231], s[22:23] offset:576
	v_mul_f32_e32 v171, v229, v229
	v_fmac_f32_e32 v171, v228, v228
	v_mul_f32_e32 v172, v231, v231
	v_fmac_f32_e32 v172, v230, v230
	v_cvt_pk_bf16_f32 v140, v228, v229
	v_cvt_pk_bf16_f32 v141, v230, v231
	global_store_dwordx2 v174, v[140:141], s[28:29] offset:288
	v_add_f32_e32 v171, v171, v172
	v_add_f32_e32 v137, v137, v171
	ds_bpermute_b32 v180, v169, v137
	v_add_u32_e32 v181, 0x80, v136
	v_lshlrev_b32_e32 v181, 2, v181
	s_waitcnt lgkmcnt(0)
	v_add_f32_e32 v137, v137, v180
	ds_bpermute_b32 v180, v170, v137
	s_waitcnt lgkmcnt(0)
	v_add_f32_e32 v137, v137, v180
	s_and_saveexec_b64 s[2:3], s[38:39]
	global_atomic_add_f32 v181, v137, s[30:31]
	s_or_b64 exec, exec, s[2:3]
	v_add_u32_e32 v157, 0xb0000, v156
	global_load_dwordx4 v[212:215], v157, s[14:15]
	global_load_dwordx4 v[216:219], v157, s[14:15] offset:64
	global_load_dwordx4 v[220:223], v157, s[14:15] offset:512
	global_load_dwordx4 v[228:231], v157, s[14:15] offset:576
	s_waitcnt vmcnt(24)
	v_add_u32_e32 v157, 0x90000, v156
	v_lshrrev_b32_e32 v174, 1, v157
	v_pk_add_f32 v[232:233], v[52:53], v[232:233]
	v_pk_add_f32 v[234:235], v[54:55], v[234:235]
	global_store_dwordx4 v157, v[232:235], s[22:23]
	v_mul_f32_e32 v137, v233, v233
	v_fmac_f32_e32 v137, v232, v232
	v_mul_f32_e32 v172, v235, v235
	v_fmac_f32_e32 v172, v234, v234
	v_cvt_pk_bf16_f32 v138, v232, v233
	v_cvt_pk_bf16_f32 v139, v234, v235
	global_store_dwordx2 v174, v[138:139], s[28:29]
	v_add_f32_e32 v137, v137, v172
	v_pk_add_f32 v[236:237], v[48:49], v[236:237]
	v_pk_add_f32 v[238:239], v[50:51], v[238:239]
	global_store_dwordx4 v157, v[236:239], s[22:23] offset:64
	v_mul_f32_e32 v171, v237, v237
	v_fmac_f32_e32 v171, v236, v236
	v_mul_f32_e32 v172, v239, v239
	v_fmac_f32_e32 v172, v238, v238
	v_cvt_pk_bf16_f32 v140, v236, v237
	v_cvt_pk_bf16_f32 v141, v238, v239
	global_store_dwordx2 v174, v[140:141], s[28:29] offset:32
	v_add_f32_e32 v171, v171, v172
	v_add_f32_e32 v137, v137, v171
	v_pk_add_f32 v[240:241], v[28:29], v[240:241]
	v_pk_add_f32 v[242:243], v[30:31], v[242:243]
	global_store_dwordx4 v157, v[240:243], s[22:23] offset:512
	v_mul_f32_e32 v171, v241, v241
	v_fmac_f32_e32 v171, v240, v240
	v_mul_f32_e32 v172, v243, v243
	v_fmac_f32_e32 v172, v242, v242
	v_cvt_pk_bf16_f32 v138, v240, v241
	v_cvt_pk_bf16_f32 v139, v242, v243
	global_store_dwordx2 v174, v[138:139], s[28:29] offset:256
	v_add_f32_e32 v171, v171, v172
	v_add_f32_e32 v137, v137, v171
	v_pk_add_f32 v[244:245], v[20:21], v[244:245]
	v_pk_add_f32 v[246:247], v[22:23], v[246:247]
	global_store_dwordx4 v157, v[244:247], s[22:23] offset:576
	v_mul_f32_e32 v171, v245, v245
	v_fmac_f32_e32 v171, v244, v244
	v_mul_f32_e32 v172, v247, v247
	v_fmac_f32_e32 v172, v246, v246
	v_cvt_pk_bf16_f32 v140, v244, v245
	v_cvt_pk_bf16_f32 v141, v246, v247
	global_store_dwordx2 v174, v[140:141], s[28:29] offset:288
	v_add_f32_e32 v171, v171, v172
	v_add_f32_e32 v137, v137, v171
	ds_bpermute_b32 v180, v169, v137
	v_add_u32_e32 v181, 0x90, v136
	v_lshlrev_b32_e32 v181, 2, v181
	s_waitcnt lgkmcnt(0)
	v_add_f32_e32 v137, v137, v180
	ds_bpermute_b32 v180, v170, v137
	s_waitcnt lgkmcnt(0)
; __device__ __forceinline__ unsigned pk2(float lo, float hi) { f32x2 v = {lo, hi}; bf16x2_t b = __builtin_convertvector(v, bf16x2_t); return __builtin_bit_cast(unsigned, b); }
;     __device__ __forceinline__ void operator()(const f32x4 (&acc)[2][2][4][2], const Unit& u, int wr, int wc, int fr, int fq) const {
;     ...
; #pragma unroll
;         for (int ai = 0; ai < 2; ++ai)
; #pragma unroll
;             for (int m = 0; m < 4; ++m) { const int row = u.pm * BM + ai * HALF + wr * 64 + m * 16 + fr; const size_t off = (size_t)row * DM + col0; float ss = 0.f;
; #pragma unroll
;                 for (int bj = 0; bj < 2; ++bj)
; #pragma unroll
;                     for (int n = 0; n < 2; ++n) { float* p = X + off + bj * HALF + n * 16; const f32x4 x = *(const f32x4*)(Xin + off + bj * HALF + n * 16) + acc[ai][bj][m][n]; *(f32x4*)p = x;
;                         ss += (x[0] * x[0] + x[1] * x[1]) + (x[2] * x[2] + x[3] * x[3]);
;                         if (XB) { u32x2 w; w.x = pk2(x[0], x[1]); w.y = pk2(x[2], x[3]); *(u32x2*)(XB + off + bj * HALF + n * 16) = w; } }
;                 if (rss_out) { ss += __shfl_xor(ss, 16); ss += __shfl_xor(ss, 32); if (fq == 0) atomicAdd(rss_out + row, ss); } }
	v_add_f32_e32 v137, v137, v180
	s_and_saveexec_b64 s[2:3], s[38:39]
	global_atomic_add_f32 v181, v137, s[30:31]
	s_or_b64 exec, exec, s[2:3]
	s_waitcnt vmcnt(20)
	v_add_u32_e32 v157, 0xa0000, v156
	v_lshrrev_b32_e32 v174, 1, v157
	v_pk_add_f32 v[192:193], v[40:41], v[192:193]
	v_pk_add_f32 v[194:195], v[42:43], v[194:195]
	global_store_dwordx4 v157, v[192:195], s[22:23]
	v_mul_f32_e32 v137, v193, v193
	v_fmac_f32_e32 v137, v192, v192
	v_mul_f32_e32 v172, v195, v195
	v_fmac_f32_e32 v172, v194, v194
	v_cvt_pk_bf16_f32 v138, v192, v193
	v_cvt_pk_bf16_f32 v139, v194, v195
	global_store_dwordx2 v174, v[138:139], s[28:29]
	v_add_f32_e32 v137, v137, v172
	v_pk_add_f32 v[200:201], v[32:33], v[200:201]
	v_pk_add_f32 v[202:203], v[34:35], v[202:203]
	global_store_dwordx4 v157, v[200:203], s[22:23] offset:64
	v_mul_f32_e32 v171, v201, v201
	v_fmac_f32_e32 v171, v200, v200
	v_mul_f32_e32 v172, v203, v203
	v_fmac_f32_e32 v172, v202, v202
	v_cvt_pk_bf16_f32 v140, v200, v201
	v_cvt_pk_bf16_f32 v141, v202, v203
	global_store_dwordx2 v174, v[140:141], s[28:29] offset:32
	v_add_f32_e32 v171, v171, v172
	v_add_f32_e32 v137, v137, v171
	v_pk_add_f32 v[204:205], v[12:13], v[204:205]
	v_pk_add_f32 v[206:207], v[14:15], v[206:207]
	global_store_dwordx4 v157, v[204:207], s[22:23] offset:512
	v_mul_f32_e32 v171, v205, v205
	v_fmac_f32_e32 v171, v204, v204
	v_mul_f32_e32 v172, v207, v207
	v_fmac_f32_e32 v172, v206, v206
	v_cvt_pk_bf16_f32 v138, v204, v205
	v_cvt_pk_bf16_f32 v139, v206, v207
	global_store_dwordx2 v174, v[138:139], s[28:29] offset:256
	v_add_f32_e32 v171, v171, v172
	v_add_f32_e32 v137, v137, v171
	v_pk_add_f32 v[208:209], v[8:9], v[208:209]
	v_pk_add_f32 v[210:211], v[10:11], v[210:211]
	global_store_dwordx4 v157, v[208:211], s[22:23] offset:576
	v_mul_f32_e32 v171, v209, v209
	v_fmac_f32_e32 v171, v208, v208
	v_mul_f32_e32 v172, v211, v211
	v_fmac_f32_e32 v172, v210, v210
	v_cvt_pk_bf16_f32 v140, v208, v209
	v_cvt_pk_bf16_f32 v141, v210, v211
	global_store_dwordx2 v174, v[140:141], s[28:29] offset:288
	v_add_f32_e32 v171, v171, v172
	v_add_f32_e32 v137, v137, v171
	ds_bpermute_b32 v180, v169, v137
	v_add_u32_e32 v181, 0xa0, v136
	v_lshlrev_b32_e32 v181, 2, v181
	s_waitcnt lgkmcnt(0)
	v_add_f32_e32 v137, v137, v180
	ds_bpermute_b32 v180, v170, v137
	s_waitcnt lgkmcnt(0)
	v_add_f32_e32 v137, v137, v180
	s_and_saveexec_b64 s[2:3], s[38:39]
	global_atomic_add_f32 v181, v137, s[30:31]
	s_or_b64 exec, exec, s[2:3]
	s_waitcnt vmcnt(16)
	v_add_u32_e32 v157, 0xb0000, v156
	v_lshrrev_b32_e32 v174, 1, v157
	v_pk_add_f32 v[212:213], v[24:25], v[212:213]
	v_pk_add_f32 v[214:215], v[26:27], v[214:215]
	global_store_dwordx4 v157, v[212:215], s[22:23]
	v_mul_f32_e32 v137, v213, v213
	v_fmac_f32_e32 v137, v212, v212
	v_mul_f32_e32 v172, v215, v215
	v_fmac_f32_e32 v172, v214, v214
	v_cvt_pk_bf16_f32 v138, v212, v213
	v_cvt_pk_bf16_f32 v139, v214, v215
	global_store_dwordx2 v174, v[138:139], s[28:29]
	v_add_f32_e32 v137, v137, v172
	v_pk_add_f32 v[216:217], v[16:17], v[216:217]
	v_pk_add_f32 v[218:219], v[18:19], v[218:219]
	global_store_dwordx4 v157, v[216:219], s[22:23] offset:64
	v_mul_f32_e32 v171, v217, v217
	v_fmac_f32_e32 v171, v216, v216
	v_mul_f32_e32 v172, v219, v219
	v_fmac_f32_e32 v172, v218, v218
	v_cvt_pk_bf16_f32 v140, v216, v217
	v_cvt_pk_bf16_f32 v141, v218, v219
	global_store_dwordx2 v174, v[140:141], s[28:29] offset:32
	v_add_f32_e32 v171, v171, v172
	v_add_f32_e32 v137, v137, v171
	v_pk_add_f32 v[220:221], v[4:5], v[220:221]
	v_pk_add_f32 v[222:223], v[6:7], v[222:223]
	global_store_dwordx4 v157, v[220:223], s[22:23] offset:512
	v_mul_f32_e32 v171, v221, v221
	v_fmac_f32_e32 v171, v220, v220
	v_mul_f32_e32 v172, v223, v223
	v_fmac_f32_e32 v172, v222, v222
	v_cvt_pk_bf16_f32 v138, v220, v221
	v_cvt_pk_bf16_f32 v139, v222, v223
	global_store_dwordx2 v174, v[138:139], s[28:29] offset:256
	v_add_f32_e32 v171, v171, v172
	v_add_f32_e32 v137, v137, v171
	v_pk_add_f32 v[228:229], v[0:1], v[228:229]
	v_pk_add_f32 v[230:231], v[2:3], v[230:231]
	global_store_dwordx4 v157, v[228:231], s[22:23] offset:576
	v_mul_f32_e32 v171, v229, v229
	v_fmac_f32_e32 v171, v228, v228
	v_mul_f32_e32 v172, v231, v231
	v_fmac_f32_e32 v172, v230, v230
	v_cvt_pk_bf16_f32 v140, v228, v229
	v_cvt_pk_bf16_f32 v141, v230, v231
	global_store_dwordx2 v174, v[140:141], s[28:29] offset:288
	v_add_f32_e32 v171, v171, v172
	v_add_f32_e32 v137, v137, v171
	ds_bpermute_b32 v180, v169, v137
	v_add_u32_e32 v181, 0xb0, v136
	v_lshlrev_b32_e32 v181, 2, v181
	s_waitcnt lgkmcnt(0)
	v_add_f32_e32 v137, v137, v180
	ds_bpermute_b32 v180, v170, v137
	s_waitcnt lgkmcnt(0)
	v_add_f32_e32 v137, v137, v180
	s_and_saveexec_b64 s[2:3], s[38:39]
	global_atomic_add_f32 v181, v137, s[30:31]
	s_or_b64 exec, exec, s[2:3]
	s_branch .LBB0_569

; __device__ __forceinline__ unsigned pk2(float lo, float hi) { f32x2 v = {lo, hi}; bf16x2_t b = __builtin_convertvector(v, bf16x2_t); return __builtin_bit_cast(unsigned, b); }
; __device__ __forceinline__ void sample_combine(const float* XinS  , float* X, const float* slab, int S, bf16_t* XB, float* rss, int gw, int NGW, int lane) {
;     for (int r = gw; r < TS; r += NGW) { const size_t row = (size_t)TP + r; float ss = 0.f;
; #pragma unroll
;         for (int j = 0; j < 4; ++j) { const int c = 4 * lane + 256 * j; f32x4 v = *(const f32x4*)(XinS + (size_t)r * DM + c);
;             for (int s = 0; s < S; ++s) v += *(const f32x4*)(slab + ((size_t)s * TS + r) * DM + c);
;             *(f32x4*)(X + row * DM + c) = v; ss += (v[0] * v[0] + v[1] * v[1]) + (v[2] * v[2] + v[3] * v[3]);
;             if (XB) { u32x2 w; w.x = pk2(v[0], v[1]); w.y = pk2(v[2], v[3]); *(u32x2*)(XB + row * DM + c) = w; } }
; #pragma unroll
;         for (int ofs = 1; ofs < 64; ofs <<= 1) ss += __shfl_xor(ss, ofs);
;         if (rss && lane == 0) rss[row] = ss; }
.LBB0_656:
	s_waitcnt lgkmcnt(0)
	v_lshl_add_u64 v[2:3], s[26:27], 0, v[152:153]
	v_lshl_add_u64 v[4:5], s[24:25], 0, v[152:153]
	v_add_co_u32_e32 v8, vcc, 0x7b00000, v2
	s_nop 1
	v_addc_co_u32_e32 v9, vcc, 0, v3, vcc
	v_add_co_u32_e32 v10, vcc, 0x7d00000, v2
	s_nop 1
	v_addc_co_u32_e32 v11, vcc, 0, v3, vcc
	v_add_co_u32_e32 v12, vcc, 0x7f00000, v2
	s_nop 1
	v_addc_co_u32_e32 v13, vcc, 0, v3, vcc
	v_add_co_u32_e32 v14, vcc, 0x8100000, v2
	s_nop 1
	v_addc_co_u32_e32 v15, vcc, 0, v3, vcc
	s_mov_b32 s11, 0x5400000
	global_load_dwordx4 v[32:35], v[4:5], off
	global_load_dwordx4 v[36:39], v[8:9], off
	global_load_dwordx4 v[40:43], v[10:11], off
	global_load_dwordx4 v[44:47], v[12:13], off
	global_load_dwordx4 v[48:51], v[14:15], off
	global_load_dwordx4 v[52:55], v[4:5], off offset:1024
	global_load_dwordx4 v[56:59], v[8:9], off offset:1024
	global_load_dwordx4 v[60:63], v[10:11], off offset:1024
	global_load_dwordx4 v[64:67], v[12:13], off offset:1024
	global_load_dwordx4 v[68:71], v[14:15], off offset:1024
	global_load_dwordx4 v[72:75], v[4:5], off offset:2048
	global_load_dwordx4 v[76:79], v[8:9], off offset:2048
	global_load_dwordx4 v[80:83], v[10:11], off offset:2048
	global_load_dwordx4 v[84:87], v[12:13], off offset:2048
	global_load_dwordx4 v[88:91], v[14:15], off offset:2048
	global_load_dwordx4 v[92:95], v[4:5], off offset:3072
	global_load_dwordx4 v[96:99], v[8:9], off offset:3072
	global_load_dwordx4 v[100:103], v[10:11], off offset:3072
	global_load_dwordx4 v[104:107], v[12:13], off offset:3072
	global_load_dwordx4 v[108:111], v[14:15], off offset:3072
	v_lshl_add_u64 v[2:3], s[22:23], 0, v[152:153]
	v_add_co_u32_e32 v2, vcc, 0x4000000, v2
	s_nop 1
	v_addc_co_u32_e32 v3, vcc, 0, v3, vcc
	v_lshl_add_u64 v[6:7], s[2:3], 0, v[0:1]
	v_add_co_u32_e32 v6, vcc, s11, v6
	s_nop 1
	v_addc_co_u32_e32 v7, vcc, 0, v7, vcc
	s_waitcnt vmcnt(0)
	v_pk_add_f32 v[32:33], v[32:33], v[36:37]
	v_pk_add_f32 v[34:35], v[34:35], v[38:39]
	v_pk_add_f32 v[32:33], v[32:33], v[40:41]
	v_pk_add_f32 v[34:35], v[34:35], v[42:43]
	v_pk_add_f32 v[32:33], v[32:33], v[44:45]
	v_pk_add_f32 v[34:35], v[34:35], v[46:47]
	v_pk_add_f32 v[32:33], v[32:33], v[48:49]
	v_pk_add_f32 v[34:35], v[34:35], v[50:51]
	global_store_dwordx4 v[2:3], v[32:35], off
	v_mul_f32_e32 v30, v33, v33
	v_mul_f32_e32 v27, v35, v35
	v_fmac_f32_e32 v30, v32, v32
	v_fmac_f32_e32 v27, v34, v34
	v_cvt_pk_bf16_f32 v22, v32, v33
	v_cvt_pk_bf16_f32 v23, v34, v35
	v_add_f32_e32 v30, v30, v27
	global_store_dwordx2 v[6:7], v[22:23], off
	v_pk_add_f32 v[52:53], v[52:53], v[56:57]
	v_pk_add_f32 v[54:55], v[54:55], v[58:59]
	v_pk_add_f32 v[52:53], v[52:53], v[60:61]
	v_pk_add_f32 v[54:55], v[54:55], v[62:63]
	v_pk_add_f32 v[52:53], v[52:53], v[64:65]
	v_pk_add_f32 v[54:55], v[54:55], v[66:67]
	v_pk_add_f32 v[52:53], v[52:53], v[68:69]
	v_pk_add_f32 v[54:55], v[54:55], v[70:71]
	global_store_dwordx4 v[2:3], v[52:55], off offset:1024
	v_mul_f32_e32 v26, v53, v53
	v_mul_f32_e32 v27, v55, v55
	v_fmac_f32_e32 v26, v52, v52
	v_fmac_f32_e32 v27, v54, v54
	v_cvt_pk_bf16_f32 v24, v52, v53
	v_cvt_pk_bf16_f32 v25, v54, v55
	v_add_f32_e32 v26, v26, v27
	global_store_dwordx2 v[6:7], v[24:25], off offset:512
	v_add_f32_e32 v30, v30, v26
	v_pk_add_f32 v[72:73], v[72:73], v[76:77]
	v_pk_add_f32 v[74:75], v[74:75], v[78:79]
	v_pk_add_f32 v[72:73], v[72:73], v[80:81]
	v_pk_add_f32 v[74:75], v[74:75], v[82:83]
	v_pk_add_f32 v[72:73], v[72:73], v[84:85]
	v_pk_add_f32 v[74:75], v[74:75], v[86:87]
	v_pk_add_f32 v[72:73], v[72:73], v[88:89]
	v_pk_add_f32 v[74:75], v[74:75], v[90:91]
	global_store_dwordx4 v[2:3], v[72:75], off offset:2048
	v_mul_f32_e32 v26, v73, v73
	v_mul_f32_e32 v27, v75, v75
	v_fmac_f32_e32 v26, v72, v72
	v_fmac_f32_e32 v27, v74, v74
	v_cvt_pk_bf16_f32 v22, v72, v73
	v_cvt_pk_bf16_f32 v23, v74, v75
	v_add_f32_e32 v26, v26, v27
	global_store_dwordx2 v[6:7], v[22:23], off offset:1024
	v_add_f32_e32 v30, v30, v26
	v_pk_add_f32 v[92:93], v[92:93], v[96:97]
	v_pk_add_f32 v[94:95], v[94:95], v[98:99]
	v_pk_add_f32 v[92:93], v[92:93], v[100:101]
	v_pk_add_f32 v[94:95], v[94:95], v[102:103]
	v_pk_add_f32 v[92:93], v[92:93], v[104:105]
	v_pk_add_f32 v[94:95], v[94:95], v[106:107]
	v_pk_add_f32 v[92:93], v[92:93], v[108:109]
	v_pk_add_f32 v[94:95], v[94:95], v[110:111]
	global_store_dwordx4 v[2:3], v[92:95], off offset:3072
	v_mul_f32_e32 v26, v93, v93
	v_mul_f32_e32 v27, v95, v95
	v_fmac_f32_e32 v26, v92, v92
	v_fmac_f32_e32 v27, v94, v94
	v_cvt_pk_bf16_f32 v24, v92, v93
	v_cvt_pk_bf16_f32 v25, v94, v95
	v_add_f32_e32 v26, v26, v27
	global_store_dwordx2 v[6:7], v[24:25], off offset:1536
	v_add_f32_e32 v30, v30, v26
	v_mov_b32_e32 v4, v30
	ds_bpermute_b32 v2, v16, v4
	s_waitcnt lgkmcnt(0)
	v_add_f32_e32 v2, v4, v2
	ds_bpermute_b32 v3, v17, v2
	s_waitcnt lgkmcnt(0)
	v_add_f32_e32 v2, v2, v3
	ds_bpermute_b32 v3, v18, v2
	s_waitcnt lgkmcnt(0)
	v_add_f32_e32 v2, v2, v3
	ds_bpermute_b32 v3, v19, v2
	s_waitcnt lgkmcnt(0)
	v_add_f32_e32 v2, v2, v3
	ds_bpermute_b32 v3, v20, v2
	s_waitcnt lgkmcnt(0)
	v_add_f32_e32 v2, v2, v3
	ds_bpermute_b32 v3, v21, v2
	s_and_saveexec_b64 s[28:29], s[38:39]
	s_cbranch_execz .LBB0_655
	s_add_u32 s18, s2, s4
	s_addc_u32 s19, s3, s10
	s_waitcnt lgkmcnt(0)
	v_add_f32_e32 v2, v2, v3
	global_store_dword v153, v2, s[18:19]
	s_branch .LBB0_655

;     __host__ __device__ bool next(int i, Unit& u) const {
;         const long L = (long)i * G + c; if (L >= nwg + nsp) return false;
;         if (L >= nwg) { const int Ls = (int)L - nwg, t = Ls / S, sl = Ls % S; u.pk = mark ? -2 : sl; u.pn = pn0 + t % nNs; u.pm = pm0 + t / nNs; u.kofs = sl * nts * BK; u.nt = nts; return true; }
;         int wgid = (int)L; { const int q = nwg / NXCD, r = nwg % NXCD, xcd = wgid % NXCD, off = wgid / NXCD; wgid = (xcd < r ? xcd * (q + 1) : r * (q + 1) + (xcd - r) * q) + off; }
;         const int nig = WGM * nN, gid = wgid / nig, fm = gid * WGM, gsz = (nM - fm) < WGM ? (nM - fm) : WGM;
;         u.pm = fm + ((wgid % nig) % gsz); u.pn = (wgid % nig) / gsz; u.pk = -1; u.kofs = 0; u.nt = nt; return true;
.LBB0_788:
	s_andn2_b64 vcc, exec, s[2:3]
	s_cbranch_vccnz .LBB0_932
	s_mov_b32 s10, s76
	s_waitcnt lgkmcnt(0)
	s_load_dwordx2 s[34:35], s[0:1], 0x98
	s_load_dwordx2 s[14:15], s[0:1], 0x90
	s_load_dwordx2 s[22:23], s[0:1], 0x90
	v_mov_b32_e32 v4, v173
	s_cmp_lt_u32 s10, 0x80
	s_cselect_b32 s24, 0x100, 0
	s_cmp_lt_u32 s10, 0x100
	s_cselect_b32 s88, 0, 0x100
	s_cmp_lt_u32 s10, 0x180
	s_cselect_b32 s88, s88, 0
	s_add_u32 s10, s10, s24
	s_sub_u32 s10, s10, s88
	s_cmpk_lt_i32 s10, 0x180
	s_cselect_b64 s[26:27], -1, 0
	s_cmpk_gt_i32 s10, 0x17f
	v_readfirstlane_b32 s36, v4
	s_cbranch_scc1 .LBB0_798
	s_cmpk_lt_i32 s10, 0x100
	s_mov_b64 s[28:29], -1
	s_cbranch_scc1 .LBB0_792
	s_bfe_u32 s11, s10, 0x40004
	s_and_b32 s4, s10, 15
	v_sub_co_u32_e64 v0, s[2:3], s11, 4
	s_and_b64 s[2:3], s[2:3], exec
	v_readfirstlane_b32 s2, v0
	s_cselect_b32 s88, s11, s2
	s_cmp_gt_u32 s11, 3
	s_cselect_b32 s24, 0x41, 64
	s_lshl_b32 s2, s4, 8
	s_mov_b64 s[28:29], 0

; #define PG8_STAGE(bufoff, gbase, voff) do { _Pragma("unroll") for (int _i = 0; _i < 2; ++_i) \
;         __builtin_amdgcn_global_load_lds((const unsigned*)((const char*)(gbase) + (voff)[_i]), (PG8_LAS unsigned*)(lds + (bufoff) + ldsw + _i * 8192), 16, 0, 0); } while (0)
; #define PG8_WAIT_V(n) asm volatile("s_waitcnt vmcnt(" #n ")" ::: "memory")
; #define PG8_BAR __builtin_amdgcn_s_barrier()
; template <class Epi, class Sched, bool ALIGN_EPI = false, bool SP2 = false>
; __device__ __forceinline__ void gemm_phase(PG8_LAS unsigned char* lds, const Gemm g, const Sched& S, const Epi& E) {
;     ...
;     const char* cA = (const char*)g.A + (size_t)cur.pm * tstepA + (size_t)(cur.kofs / BK) * kstepA; const char* cB = (const char*)g.Bt + (size_t)cur.pn * tstep + (size_t)cur.kofs * 2;
;     S.a_ready(cur);
;     if constexpr (SP2) {
;         PG8_STAGE(PG8_SB(0, 0), cB, voffB); PG8_STAGE(PG8_SB(0, 1), cB + hstep, voffB); PG8_STAGE(PG8_SA(0, 0), cA, voffA); PG8_STAGE(PG8_SA(0, 1), cA + hstepA, voffA);
;         if (wr == 1) PG8_BAR;
;         PG8_WAIT_V(2); PG8_BAR;
;         PG8_STAGE(PG8_SB(1, 0), cB + kstep, voffB); PG8_STAGE(PG8_SA(1, 0), cA + kstepA, voffA); PG8_STAGE(PG8_SB(1, 1), cB + hstep + kstep, voffB);
;         PG8_WAIT_V(6); PG8_BAR;
;     } else {
;         PG8_STAGE(PG8_SB(0, 0), cB, voffB); PG8_STAGE(PG8_SA(0, 0), cA, voffA); PG8_STAGE(PG8_SB(0, 1), cB + hstep, voffB); PG8_STAGE(PG8_SA(0, 1), cA + hstepA, voffA);
;         if (wr == 1) PG8_BAR;
;         PG8_WAIT_V(4); PG8_BAR;
;         PG8_STAGE(PG8_SB(1, 0), cB + kstep, voffB); PG8_STAGE(PG8_SA(1, 0), cA + kstepA, voffA); PG8_STAGE(PG8_SB(1, 1), cB + hstep + kstep, voffB);
;         PG8_WAIT_V(6); PG8_BAR;
; __global__ void __launch_bounds__(NWAVES * 64, 2) fwd_mega(Args args) {
;     ...
;             pg8::Gemm g{(const bf16_t*)(ws + WS_H), (const bf16_t*)(ws + WS_W + (size_t)l * W_LAYER + W_FF2), MT, DM, DFF, DFF, 64, (size_t)256 * 64 * 2, (size_t)256 * DFF * 2};   pg8::StaticOrder S; int bxo = blockIdx.x; asm volatile("" : "+s"(bxo)); S.init(TP, DM, DFF, G, bxo); S.split(TP / 256, TS / 256, SPLIT6, DFF);
;             pg8::EpiRes E{KOUT, KOUT, (l + 1 < DEPTH) ? (bf16_t*)(ws + WS_XB) : nullptr, (l + 1 < DEPTH) ? (float*)(ws + WS_RSS) + (size_t)(2 * l + 2) * MT : nullptr, (float*)(ws + WS_KS + (size_t)l * KS_LAYER)};
;             pg8::gemm_phase<pg8::EpiRes, pg8::StaticOrder, true, true>(lds, g, S, E);
.LBB0_801:
	s_add_u32 s28, s34, 0x3400000
	s_mul_i32 s30, s62, 0x8400
	s_mov_b32 s31, s5
	s_addc_u32 s29, s35, 0
	s_lshl_b64 s[30:31], s[30:31], 2
	s_add_u32 s30, s34, s30
	s_addc_u32 s31, s35, s31
	s_add_u32 s30, s30, 0x5521000
	s_addc_u32 s31, s31, 0
	s_mov_b32 s39, 0
	s_add_u32 s34, s34, s39
	s_addc_u32 s35, s35, 0
	s_add_u32 s61, s34, 0x5900000
	s_mov_b32 s16, s62
	s_addc_u32 s62, s35, 0
	s_lshl_b32 s34, s38, 5
	s_and_b32 s41, s34, 0x60
	s_add_i32 m0, s25, 0x18000
	v_lshl_add_u64 v[0:1], v[0:1], 0, s[12:13]
	s_lshl_b32 s40, s37, 6
	s_lshl_b32 s37, s37, 13
	s_lshl_b32 s38, s41, 7
	s_waitcnt vmcnt(2)
	s_barrier
	global_load_lds_dwordx4 v[0:1], off
	s_add_i32 m0, s25, 0x1a000
	s_add_u32 s34, s2, 0x8000
	v_mov_b32_e32 v133, v153
	v_lshl_add_u64 v[0:1], v[2:3], 0, s[12:13]
	s_addc_u32 s35, s3, 0
	s_add_i32 s63, s25, 0x8000
	v_mov_b32_e32 v135, v153
	global_load_lds_dwordx4 v[0:1], off
	v_lshl_add_u64 v[0:1], s[34:35], 0, v[132:133]
	s_mov_b32 m0, s63
	s_add_i32 s64, s25, 0xa000
	global_load_lds_dwordx4 v[0:1], off
	v_lshl_add_u64 v[0:1], s[34:35], 0, v[134:135]
	s_add_u32 s34, s90, 0x100080
	s_mov_b32 m0, s64
	s_addc_u32 s35, s91, 0
	global_load_lds_dwordx4 v[0:1], off
	s_add_i32 m0, s25, 0x1c000
	v_lshl_add_u64 v[0:1], s[34:35], 0, v[152:153]
	global_load_lds_dwordx4 v[0:1], off
	v_lshl_add_u64 v[0:1], s[34:35], 0, v[136:137]
	s_add_i32 m0, s25, 0x1e000
	s_cmpk_lt_u32 s36, 0x100
	global_load_lds_dwordx4 v[0:1], off
	v_and_b32_e32 v0, 15, v4
	v_bfe_u32 v1, v4, 4, 2
	v_or_b32_e32 v170, s40, v0
	v_lshlrev_b32_e32 v2, 4, v1
	s_cselect_b64 s[34:35], -1, 0
	s_addk_i32 s40, 0xc000
	v_lshl_or_b32 v2, v0, 6, v2
	v_lshlrev_b32_e32 v3, 2, v4
	v_or_b32_e32 v178, s40, v0
	v_lshlrev_b32_e32 v0, 10, v5
	v_and_b32_e32 v3, 32, v3
	v_and_b32_e32 v0, 0xfffff800, v0
	v_bitop3_b32 v171, v2, s38, v3 bitop3:0xde
	v_cmp_eq_u32_e64 s[38:39], 0, v1
	v_lshl_or_b32 v183, v1, 2, s41
	v_lshl_add_u32 v0, v6, 7, v0
	v_and_b32_e32 v1, 1, v5
	v_lshl_or_b32 v0, v1, 6, v0
	v_lshl_add_u32 v138, v7, 1, v0
	v_lshlrev_b32_e32 v0, 10, v8
	v_and_b32_e32 v0, 0xfffff800, v0
	s_waitcnt vmcnt(6)
	v_lshl_add_u32 v0, v9, 7, v0
	v_and_b32_e32 v1, 1, v8
	v_bitop3_b32 v4, v2, s37, v3 bitop3:0xde
	v_lshl_or_b32 v0, v1, 6, v0
	s_mov_b32 s65, 0
	v_or_b32_e32 v172, 16, v170
	v_or_b32_e32 v174, 32, v170
	v_or_b32_e32 v176, 48, v170
	v_or_b32_e32 v180, 16, v178
	v_or_b32_e32 v181, 32, v178
	v_or_b32_e32 v182, 48, v178
	s_ashr_i32 s66, s10, 31
	v_mov_b32_e32 v139, v153
	v_lshl_add_u32 v140, v10, 1, v0
	v_mov_b32_e32 v141, v153
	v_add_u32_e32 v184, 0, v4
	s_barrier
	s_branch .LBB0_804

;     __host__ __device__ bool next(int i, Unit& u) const {
;         const long L = (long)i * G + c; if (L >= nwg + nsp) return false;
;         if (L >= nwg) { const int Ls = (int)L - nwg, t = Ls / S, sl = Ls % S; u.pk = mark ? -2 : sl; u.pn = pn0 + t % nNs; u.pm = pm0 + t / nNs; u.kofs = sl * nts * BK; u.nt = nts; return true; }
;         int wgid = (int)L; { const int q = nwg / NXCD, r = nwg % NXCD, xcd = wgid % NXCD, off = wgid / NXCD; wgid = (xcd < r ? xcd * (q + 1) : r * (q + 1) + (xcd - r) * q) + off; }
;         const int nig = WGM * nN, gid = wgid / nig, fm = gid * WGM, gsz = (nM - fm) < WGM ? (nM - fm) : WGM;
;         u.pm = fm + ((wgid % nig) % gsz); u.pn = (wgid % nig) / gsz; u.pk = -1; u.kofs = 0; u.nt = nt; return true;
.LBB0_804:
	s_mov_b32 s10, s76
	s_add_i32 s65, s65, 1
	s_mul_i32 s37, s65, s48
	s_mul_hi_u32 s40, s65, s33
	s_add_i32 s37, s40, s37
	s_mul_i32 s40, s65, s33
	s_add_u32 s40, s40, s10
	s_addc_u32 s41, s37, s66
	s_cmp_lt_u32 s40, 0x180
	s_cselect_b64 s[42:43], -1, 0
	s_cmp_gt_u32 s40, 0x17f
	s_cselect_b64 vcc, -1, 0
	s_cbranch_vccnz .LBB0_813
	s_cmp_lt_u32 s40, 0x80
	s_cselect_b32 s36, 0x100, 0
	s_cmp_lt_u32 s40, 0x100
	s_cselect_b32 s37, 0, 0x100
	s_cmp_lt_u32 s40, 0x180
	s_cselect_b32 s37, s37, 0
	s_add_u32 s40, s40, s36
	s_sub_u32 s40, s40, s37
	v_cmp_lt_i64_e32 vcc, s[40:41], v[162:163]
	s_mov_b64 s[50:51], -1
	s_and_b64 vcc, exec, vcc
	s_cbranch_vccnz .LBB0_807
	s_add_i32 s36, s40, 0xffffff00
	s_and_b32 s68, s36, 15
	s_lshr_b32 s44, s36, 4
	s_lshr_b32 s46, s36, 6
	s_and_b32 s44, s44, 3
	s_add_i32 s46, s46, 64
	s_lshl_b32 s36, s68, 8
	s_mov_b64 s[50:51], 0
.LBB0_807:
	s_andn2_b64 vcc, exec, s[50:51]
	s_mov_b32 s67, 4
	s_cbranch_vccnz .LBB0_813
	s_ashr_i32 s36, s40, 31
	s_lshr_b32 s36, s36, 29
	s_add_i32 s41, s40, s36
	s_and_b32 s36, s41, -8
	s_sub_i32 s40, s40, s36
	s_cmp_gt_i32 s40, -1
	s_mov_b64 s[36:37], -1
	s_cbranch_scc0 .LBB0_810
	s_lshl_b32 s44, s40, 5
	s_mov_b64 s[36:37], 0

; __device__ __forceinline__ unsigned pk2(float lo, float hi) { f32x2 v = {lo, hi}; bf16x2_t b = __builtin_convertvector(v, bf16x2_t); return __builtin_bit_cast(unsigned, b); }
;     __device__ __forceinline__ void operator()(const f32x4 (&acc)[2][2][4][2], const Unit& u, int wr, int wc, int fr, int fq) const {
;     ...
; #pragma unroll
;         for (int ai = 0; ai < 2; ++ai)
; #pragma unroll
;             for (int m = 0; m < 4; ++m) { const int row = u.pm * BM + ai * HALF + wr * 64 + m * 16 + fr; const size_t off = (size_t)row * DM + col0; float ss = 0.f;
; #pragma unroll
;                 for (int bj = 0; bj < 2; ++bj)
; #pragma unroll
;                     for (int n = 0; n < 2; ++n) { float* p = X + off + bj * HALF + n * 16; const f32x4 x = *(const f32x4*)(Xin + off + bj * HALF + n * 16) + acc[ai][bj][m][n]; *(f32x4*)p = x;
;                         ss += (x[0] * x[0] + x[1] * x[1]) + (x[2] * x[2] + x[3] * x[3]);
;                         if (XB) { u32x2 w; w.x = pk2(x[0], x[1]); w.y = pk2(x[2], x[3]); *(u32x2*)(XB + off + bj * HALF + n * 16) = w; } }
;                 if (rss_out) { ss += __shfl_xor(ss, 16); ss += __shfl_xor(ss, 32); if (fq == 0) atomicAdd(rss_out + row, ss); } }
.LBB0_824:
	s_and_b64 vcc, exec, s[20:21]
	s_cbranch_vccnz .Lp6_plain
	s_lshl_b32 s37, s24, 8
	v_add_u32_e32 v144, s37, v170
	v_lshl_add_u32 v186, v144, 10, v142
	v_lshlrev_b32_e32 v186, 2, v186
	global_load_dwordx4 v[192:195], v186, s[14:15]
	global_load_dwordx4 v[200:203], v186, s[14:15] offset:64
	global_load_dwordx4 v[204:207], v186, s[14:15] offset:512
	global_load_dwordx4 v[208:211], v186, s[14:15] offset:576
	v_add_u32_e32 v187, 0x10000, v186
	global_load_dwordx4 v[212:215], v187, s[14:15]
	global_load_dwordx4 v[216:219], v187, s[14:15] offset:64
	global_load_dwordx4 v[220:223], v187, s[14:15] offset:512
	global_load_dwordx4 v[228:231], v187, s[14:15] offset:576
	v_add_u32_e32 v187, 0x20000, v186
	global_load_dwordx4 v[232:235], v187, s[14:15]
	global_load_dwordx4 v[236:239], v187, s[14:15] offset:64
	global_load_dwordx4 v[240:243], v187, s[14:15] offset:512
	global_load_dwordx4 v[244:247], v187, s[14:15] offset:576
	v_xor_b32_e32 v128, 16, v191
	v_xor_b32_e32 v129, 32, v191
	v_lshlrev_b32_e32 v128, 2, v128
	v_lshlrev_b32_e32 v129, 2, v129
	s_waitcnt vmcnt(8)
	v_lshrrev_b32_e32 v188, 1, v186
	v_pk_add_f32 v[192:193], v[124:125], v[192:193]
	v_pk_add_f32 v[194:195], v[126:127], v[194:195]
	global_store_dwordx4 v186, v[192:195], s[22:23]
	v_mul_f32_e32 v145, v193, v193
	v_fmac_f32_e32 v145, v192, v192
	v_mul_f32_e32 v147, v195, v195
	v_fmac_f32_e32 v147, v194, v194
	v_cvt_pk_bf16_f32 v148, v192, v193
	v_cvt_pk_bf16_f32 v149, v194, v195
	global_store_dwordx2 v188, v[148:149], s[28:29]
	v_add_f32_e32 v145, v145, v147
	v_pk_add_f32 v[200:201], v[120:121], v[200:201]
	v_pk_add_f32 v[202:203], v[122:123], v[202:203]
	global_store_dwordx4 v186, v[200:203], s[22:23] offset:64
	v_mul_f32_e32 v146, v201, v201
	v_fmac_f32_e32 v146, v200, v200
	v_mul_f32_e32 v147, v203, v203
	v_fmac_f32_e32 v147, v202, v202
	v_cvt_pk_bf16_f32 v150, v200, v201
	v_cvt_pk_bf16_f32 v151, v202, v203
	global_store_dwordx2 v188, v[150:151], s[28:29] offset:32
	v_add_f32_e32 v146, v146, v147
	v_add_f32_e32 v145, v145, v146
	v_pk_add_f32 v[204:205], v[108:109], v[204:205]
	v_pk_add_f32 v[206:207], v[110:111], v[206:207]
	global_store_dwordx4 v186, v[204:207], s[22:23] offset:512
	v_mul_f32_e32 v146, v205, v205
	v_fmac_f32_e32 v146, v204, v204
	v_mul_f32_e32 v147, v207, v207
	v_fmac_f32_e32 v147, v206, v206
	v_cvt_pk_bf16_f32 v148, v204, v205
	v_cvt_pk_bf16_f32 v149, v206, v207
	global_store_dwordx2 v188, v[148:149], s[28:29] offset:256
	v_add_f32_e32 v146, v146, v147
	v_add_f32_e32 v145, v145, v146
	v_pk_add_f32 v[208:209], v[100:101], v[208:209]
	v_pk_add_f32 v[210:211], v[102:103], v[210:211]
	global_store_dwordx4 v186, v[208:211], s[22:23] offset:576
	v_mul_f32_e32 v146, v209, v209
	v_fmac_f32_e32 v146, v208, v208
	v_mul_f32_e32 v147, v211, v211
	v_fmac_f32_e32 v147, v210, v210
	v_cvt_pk_bf16_f32 v150, v208, v209
	v_cvt_pk_bf16_f32 v151, v210, v211
	global_store_dwordx2 v188, v[150:151], s[28:29] offset:288
	v_add_f32_e32 v146, v146, v147
	v_add_f32_e32 v145, v145, v146
	ds_bpermute_b32 v130, v128, v145
	v_add_u32_e32 v131, 0x0, v144
	v_lshlrev_b32_e32 v131, 2, v131
	s_waitcnt lgkmcnt(0)
	v_add_f32_e32 v145, v145, v130
	ds_bpermute_b32 v130, v129, v145
	s_waitcnt lgkmcnt(0)
	v_add_f32_e32 v145, v145, v130
	s_and_saveexec_b64 s[2:3], s[38:39]
	global_atomic_add_f32 v131, v145, s[30:31]
	s_or_b64 exec, exec, s[2:3]
	v_add_u32_e32 v187, 0x30000, v186
	global_load_dwordx4 v[192:195], v187, s[14:15]
	global_load_dwordx4 v[200:203], v187, s[14:15] offset:64
	global_load_dwordx4 v[204:207], v187, s[14:15] offset:512
	global_load_dwordx4 v[208:211], v187, s[14:15] offset:576
	s_waitcnt vmcnt(16)
	v_add_u32_e32 v187, 0x10000, v186
	v_lshrrev_b32_e32 v188, 1, v187
	v_pk_add_f32 v[212:213], v[116:117], v[212:213]
	v_pk_add_f32 v[214:215], v[118:119], v[214:215]
	global_store_dwordx4 v187, v[212:215], s[22:23]
	v_mul_f32_e32 v145, v213, v213
	v_fmac_f32_e32 v145, v212, v212
	v_mul_f32_e32 v147, v215, v215
	v_fmac_f32_e32 v147, v214, v214
	v_cvt_pk_bf16_f32 v148, v212, v213
	v_cvt_pk_bf16_f32 v149, v214, v215
	global_store_dwordx2 v188, v[148:149], s[28:29]
	v_add_f32_e32 v145, v145, v147
	v_pk_add_f32 v[216:217], v[112:113], v[216:217]
	v_pk_add_f32 v[218:219], v[114:115], v[218:219]
	global_store_dwordx4 v187, v[216:219], s[22:23] offset:64
	v_mul_f32_e32 v146, v217, v217
	v_fmac_f32_e32 v146, v216, v216
	v_mul_f32_e32 v147, v219, v219
	v_fmac_f32_e32 v147, v218, v218
	v_cvt_pk_bf16_f32 v150, v216, v217
	v_cvt_pk_bf16_f32 v151, v218, v219
	global_store_dwordx2 v188, v[150:151], s[28:29] offset:32
	v_add_f32_e32 v146, v146, v147
	v_add_f32_e32 v145, v145, v146
	v_pk_add_f32 v[220:221], v[92:93], v[220:221]
	v_pk_add_f32 v[222:223], v[94:95], v[222:223]
	global_store_dwordx4 v187, v[220:223], s[22:23] offset:512
	v_mul_f32_e32 v146, v221, v221
	v_fmac_f32_e32 v146, v220, v220
	v_mul_f32_e32 v147, v223, v223
	v_fmac_f32_e32 v147, v222, v222
	v_cvt_pk_bf16_f32 v148, v220, v221
	v_cvt_pk_bf16_f32 v149, v222, v223
	global_store_dwordx2 v188, v[148:149], s[28:29] offset:256
	v_add_f32_e32 v146, v146, v147
	v_add_f32_e32 v145, v145, v146
	v_pk_add_f32 v[228:229], v[84:85], v[228:229]
	v_pk_add_f32 v[230:231], v[86:87], v[230:231]
	global_store_dwordx4 v187, v[228:231], s[22:23] offset:576
	v_mul_f32_e32 v146, v229, v229
	v_fmac_f32_e32 v146, v228, v228
	v_mul_f32_e32 v147, v231, v231
	v_fmac_f32_e32 v147, v230, v230
	v_cvt_pk_bf16_f32 v150, v228, v229
	v_cvt_pk_bf16_f32 v151, v230, v231
	global_store_dwordx2 v188, v[150:151], s[28:29] offset:288
	v_add_f32_e32 v146, v146, v147
	v_add_f32_e32 v145, v145, v146
	ds_bpermute_b32 v130, v128, v145
	v_add_u32_e32 v131, 0x10, v144
	v_lshlrev_b32_e32 v131, 2, v131
	s_waitcnt lgkmcnt(0)
; __device__ __forceinline__ unsigned pk2(float lo, float hi) { f32x2 v = {lo, hi}; bf16x2_t b = __builtin_convertvector(v, bf16x2_t); return __builtin_bit_cast(unsigned, b); }
;     __device__ __forceinline__ void operator()(const f32x4 (&acc)[2][2][4][2], const Unit& u, int wr, int wc, int fr, int fq) const {
;     ...
; #pragma unroll
;         for (int ai = 0; ai < 2; ++ai)
; #pragma unroll
;             for (int m = 0; m < 4; ++m) { const int row = u.pm * BM + ai * HALF + wr * 64 + m * 16 + fr; const size_t off = (size_t)row * DM + col0; float ss = 0.f;
; #pragma unroll
;                 for (int bj = 0; bj < 2; ++bj)
; #pragma unroll
;                     for (int n = 0; n < 2; ++n) { float* p = X + off + bj * HALF + n * 16; const f32x4 x = *(const f32x4*)(Xin + off + bj * HALF + n * 16) + acc[ai][bj][m][n]; *(f32x4*)p = x;
;                         ss += (x[0] * x[0] + x[1] * x[1]) + (x[2] * x[2] + x[3] * x[3]);
;                         if (XB) { u32x2 w; w.x = pk2(x[0], x[1]); w.y = pk2(x[2], x[3]); *(u32x2*)(XB + off + bj * HALF + n * 16) = w; } }
;                 if (rss_out) { ss += __shfl_xor(ss, 16); ss += __shfl_xor(ss, 32); if (fq == 0) atomicAdd(rss_out + row, ss); } }
	v_add_f32_e32 v145, v145, v130
	ds_bpermute_b32 v130, v129, v145
	s_waitcnt lgkmcnt(0)
	v_add_f32_e32 v145, v145, v130
	s_and_saveexec_b64 s[2:3], s[38:39]
	global_atomic_add_f32 v131, v145, s[30:31]
	s_or_b64 exec, exec, s[2:3]
	v_add_u32_e32 v187, 0x80000, v186
	global_load_dwordx4 v[212:215], v187, s[14:15]
	global_load_dwordx4 v[216:219], v187, s[14:15] offset:64
	global_load_dwordx4 v[220:223], v187, s[14:15] offset:512
	global_load_dwordx4 v[228:231], v187, s[14:15] offset:576
	s_waitcnt vmcnt(24)
	v_add_u32_e32 v187, 0x20000, v186
	v_lshrrev_b32_e32 v188, 1, v187
	v_pk_add_f32 v[232:233], v[104:105], v[232:233]
	v_pk_add_f32 v[234:235], v[106:107], v[234:235]
	global_store_dwordx4 v187, v[232:235], s[22:23]
	v_mul_f32_e32 v145, v233, v233
	v_fmac_f32_e32 v145, v232, v232
	v_mul_f32_e32 v147, v235, v235
	v_fmac_f32_e32 v147, v234, v234
	v_cvt_pk_bf16_f32 v148, v232, v233
	v_cvt_pk_bf16_f32 v149, v234, v235
	global_store_dwordx2 v188, v[148:149], s[28:29]
	v_add_f32_e32 v145, v145, v147
	v_pk_add_f32 v[236:237], v[96:97], v[236:237]
	v_pk_add_f32 v[238:239], v[98:99], v[238:239]
	global_store_dwordx4 v187, v[236:239], s[22:23] offset:64
	v_mul_f32_e32 v146, v237, v237
	v_fmac_f32_e32 v146, v236, v236
	v_mul_f32_e32 v147, v239, v239
	v_fmac_f32_e32 v147, v238, v238
	v_cvt_pk_bf16_f32 v150, v236, v237
	v_cvt_pk_bf16_f32 v151, v238, v239
	global_store_dwordx2 v188, v[150:151], s[28:29] offset:32
	v_add_f32_e32 v146, v146, v147
	v_add_f32_e32 v145, v145, v146
	v_pk_add_f32 v[240:241], v[76:77], v[240:241]
	v_pk_add_f32 v[242:243], v[78:79], v[242:243]
	global_store_dwordx4 v187, v[240:243], s[22:23] offset:512
	v_mul_f32_e32 v146, v241, v241
	v_fmac_f32_e32 v146, v240, v240
	v_mul_f32_e32 v147, v243, v243
	v_fmac_f32_e32 v147, v242, v242
	v_cvt_pk_bf16_f32 v148, v240, v241
	v_cvt_pk_bf16_f32 v149, v242, v243
	global_store_dwordx2 v188, v[148:149], s[28:29] offset:256
	v_add_f32_e32 v146, v146, v147
	v_add_f32_e32 v145, v145, v146
	v_pk_add_f32 v[244:245], v[72:73], v[244:245]
	v_pk_add_f32 v[246:247], v[74:75], v[246:247]
	global_store_dwordx4 v187, v[244:247], s[22:23] offset:576
	v_mul_f32_e32 v146, v245, v245
	v_fmac_f32_e32 v146, v244, v244
	v_mul_f32_e32 v147, v247, v247
	v_fmac_f32_e32 v147, v246, v246
	v_cvt_pk_bf16_f32 v150, v244, v245
	v_cvt_pk_bf16_f32 v151, v246, v247
	global_store_dwordx2 v188, v[150:151], s[28:29] offset:288
	v_add_f32_e32 v146, v146, v147
	v_add_f32_e32 v145, v145, v146
	ds_bpermute_b32 v130, v128, v145
	v_add_u32_e32 v131, 0x20, v144
	v_lshlrev_b32_e32 v131, 2, v131
	s_waitcnt lgkmcnt(0)
	v_add_f32_e32 v145, v145, v130
	ds_bpermute_b32 v130, v129, v145
	s_waitcnt lgkmcnt(0)
	v_add_f32_e32 v145, v145, v130
	s_and_saveexec_b64 s[2:3], s[38:39]
	global_atomic_add_f32 v131, v145, s[30:31]
	s_or_b64 exec, exec, s[2:3]
	v_add_u32_e32 v187, 0x90000, v186
	global_load_dwordx4 v[232:235], v187, s[14:15]
	global_load_dwordx4 v[236:239], v187, s[14:15] offset:64
	global_load_dwordx4 v[240:243], v187, s[14:15] offset:512
	global_load_dwordx4 v[244:247], v187, s[14:15] offset:576
	s_waitcnt vmcnt(24)
	v_add_u32_e32 v187, 0x30000, v186
	v_lshrrev_b32_e32 v188, 1, v187
	v_pk_add_f32 v[192:193], v[88:89], v[192:193]
	v_pk_add_f32 v[194:195], v[90:91], v[194:195]
	global_store_dwordx4 v187, v[192:195], s[22:23]
	v_mul_f32_e32 v145, v193, v193
	v_fmac_f32_e32 v145, v192, v192
	v_mul_f32_e32 v147, v195, v195
	v_fmac_f32_e32 v147, v194, v194
	v_cvt_pk_bf16_f32 v148, v192, v193
	v_cvt_pk_bf16_f32 v149, v194, v195
	global_store_dwordx2 v188, v[148:149], s[28:29]
	v_add_f32_e32 v145, v145, v147
	v_pk_add_f32 v[200:201], v[80:81], v[200:201]
	v_pk_add_f32 v[202:203], v[82:83], v[202:203]
	global_store_dwordx4 v187, v[200:203], s[22:23] offset:64
	v_mul_f32_e32 v146, v201, v201
	v_fmac_f32_e32 v146, v200, v200
	v_mul_f32_e32 v147, v203, v203
	v_fmac_f32_e32 v147, v202, v202
	v_cvt_pk_bf16_f32 v150, v200, v201
	v_cvt_pk_bf16_f32 v151, v202, v203
	global_store_dwordx2 v188, v[150:151], s[28:29] offset:32
	v_add_f32_e32 v146, v146, v147
	v_add_f32_e32 v145, v145, v146
	v_pk_add_f32 v[204:205], v[68:69], v[204:205]
	v_pk_add_f32 v[206:207], v[70:71], v[206:207]
	global_store_dwordx4 v187, v[204:207], s[22:23] offset:512
	v_mul_f32_e32 v146, v205, v205
	v_fmac_f32_e32 v146, v204, v204
	v_mul_f32_e32 v147, v207, v207
	v_fmac_f32_e32 v147, v206, v206
	v_cvt_pk_bf16_f32 v148, v204, v205
	v_cvt_pk_bf16_f32 v149, v206, v207
	global_store_dwordx2 v188, v[148:149], s[28:29] offset:256
	v_add_f32_e32 v146, v146, v147
	v_add_f32_e32 v145, v145, v146
	v_pk_add_f32 v[208:209], v[64:65], v[208:209]
	v_pk_add_f32 v[210:211], v[66:67], v[210:211]
	global_store_dwordx4 v187, v[208:211], s[22:23] offset:576
	v_mul_f32_e32 v146, v209, v209
	v_fmac_f32_e32 v146, v208, v208
	v_mul_f32_e32 v147, v211, v211
	v_fmac_f32_e32 v147, v210, v210
	v_cvt_pk_bf16_f32 v150, v208, v209
	v_cvt_pk_bf16_f32 v151, v210, v211
	global_store_dwordx2 v188, v[150:151], s[28:29] offset:288
	v_add_f32_e32 v146, v146, v147
	v_add_f32_e32 v145, v145, v146
	ds_bpermute_b32 v130, v128, v145
	v_add_u32_e32 v131, 0x30, v144
	v_lshlrev_b32_e32 v131, 2, v131
	s_waitcnt lgkmcnt(0)
	v_add_f32_e32 v145, v145, v130
	ds_bpermute_b32 v130, v129, v145
	s_waitcnt lgkmcnt(0)
	v_add_f32_e32 v145, v145, v130
	s_and_saveexec_b64 s[2:3], s[38:39]
	global_atomic_add_f32 v131, v145, s[30:31]
	s_or_b64 exec, exec, s[2:3]
	v_add_u32_e32 v187, 0xa0000, v186
	global_load_dwordx4 v[192:195], v187, s[14:15]
	global_load_dwordx4 v[200:203], v187, s[14:15] offset:64
	global_load_dwordx4 v[204:207], v187, s[14:15] offset:512
	global_load_dwordx4 v[208:211], v187, s[14:15] offset:576
	s_waitcnt vmcnt(24)
; __device__ __forceinline__ unsigned pk2(float lo, float hi) { f32x2 v = {lo, hi}; bf16x2_t b = __builtin_convertvector(v, bf16x2_t); return __builtin_bit_cast(unsigned, b); }
;     __device__ __forceinline__ void operator()(const f32x4 (&acc)[2][2][4][2], const Unit& u, int wr, int wc, int fr, int fq) const {
;     ...
; #pragma unroll
;         for (int ai = 0; ai < 2; ++ai)
; #pragma unroll
;             for (int m = 0; m < 4; ++m) { const int row = u.pm * BM + ai * HALF + wr * 64 + m * 16 + fr; const size_t off = (size_t)row * DM + col0; float ss = 0.f;
; #pragma unroll
;                 for (int bj = 0; bj < 2; ++bj)
; #pragma unroll
;                     for (int n = 0; n < 2; ++n) { float* p = X + off + bj * HALF + n * 16; const f32x4 x = *(const f32x4*)(Xin + off + bj * HALF + n * 16) + acc[ai][bj][m][n]; *(f32x4*)p = x;
;                         ss += (x[0] * x[0] + x[1] * x[1]) + (x[2] * x[2] + x[3] * x[3]);
;                         if (XB) { u32x2 w; w.x = pk2(x[0], x[1]); w.y = pk2(x[2], x[3]); *(u32x2*)(XB + off + bj * HALF + n * 16) = w; } }
;                 if (rss_out) { ss += __shfl_xor(ss, 16); ss += __shfl_xor(ss, 32); if (fq == 0) atomicAdd(rss_out + row, ss); } }
	v_add_u32_e32 v187, 0x80000, v186
	v_lshrrev_b32_e32 v188, 1, v187
	v_pk_add_f32 v[212:213], v[60:61], v[212:213]
	v_pk_add_f32 v[214:215], v[62:63], v[214:215]
	global_store_dwordx4 v187, v[212:215], s[22:23]
	v_mul_f32_e32 v145, v213, v213
	v_fmac_f32_e32 v145, v212, v212
	v_mul_f32_e32 v147, v215, v215
	v_fmac_f32_e32 v147, v214, v214
	v_cvt_pk_bf16_f32 v148, v212, v213
	v_cvt_pk_bf16_f32 v149, v214, v215
	global_store_dwordx2 v188, v[148:149], s[28:29]
	v_add_f32_e32 v145, v145, v147
	v_pk_add_f32 v[216:217], v[56:57], v[216:217]
	v_pk_add_f32 v[218:219], v[58:59], v[218:219]
	global_store_dwordx4 v187, v[216:219], s[22:23] offset:64
	v_mul_f32_e32 v146, v217, v217
	v_fmac_f32_e32 v146, v216, v216
	v_mul_f32_e32 v147, v219, v219
	v_fmac_f32_e32 v147, v218, v218
	v_cvt_pk_bf16_f32 v150, v216, v217
	v_cvt_pk_bf16_f32 v151, v218, v219
	global_store_dwordx2 v188, v[150:151], s[28:29] offset:32
	v_add_f32_e32 v146, v146, v147
	v_add_f32_e32 v145, v145, v146
	v_pk_add_f32 v[220:221], v[44:45], v[220:221]
	v_pk_add_f32 v[222:223], v[46:47], v[222:223]
	global_store_dwordx4 v187, v[220:223], s[22:23] offset:512
	v_mul_f32_e32 v146, v221, v221
	v_fmac_f32_e32 v146, v220, v220
	v_mul_f32_e32 v147, v223, v223
	v_fmac_f32_e32 v147, v222, v222
	v_cvt_pk_bf16_f32 v148, v220, v221
	v_cvt_pk_bf16_f32 v149, v222, v223
	global_store_dwordx2 v188, v[148:149], s[28:29] offset:256
	v_add_f32_e32 v146, v146, v147
	v_add_f32_e32 v145, v145, v146
	v_pk_add_f32 v[228:229], v[36:37], v[228:229]
	v_pk_add_f32 v[230:231], v[38:39], v[230:231]
	global_store_dwordx4 v187, v[228:231], s[22:23] offset:576
	v_mul_f32_e32 v146, v229, v229
	v_fmac_f32_e32 v146, v228, v228
	v_mul_f32_e32 v147, v231, v231
	v_fmac_f32_e32 v147, v230, v230
	v_cvt_pk_bf16_f32 v150, v228, v229
	v_cvt_pk_bf16_f32 v151, v230, v231
	global_store_dwordx2 v188, v[150:151], s[28:29] offset:288
	v_add_f32_e32 v146, v146, v147
	v_add_f32_e32 v145, v145, v146
	ds_bpermute_b32 v130, v128, v145
	v_add_u32_e32 v131, 0x80, v144
	v_lshlrev_b32_e32 v131, 2, v131
	s_waitcnt lgkmcnt(0)
	v_add_f32_e32 v145, v145, v130
	ds_bpermute_b32 v130, v129, v145
	s_waitcnt lgkmcnt(0)
	v_add_f32_e32 v145, v145, v130
	s_and_saveexec_b64 s[2:3], s[38:39]
	global_atomic_add_f32 v131, v145, s[30:31]
	s_or_b64 exec, exec, s[2:3]
	v_add_u32_e32 v187, 0xb0000, v186
	global_load_dwordx4 v[212:215], v187, s[14:15]
	global_load_dwordx4 v[216:219], v187, s[14:15] offset:64
	global_load_dwordx4 v[220:223], v187, s[14:15] offset:512
	global_load_dwordx4 v[228:231], v187, s[14:15] offset:576
	s_waitcnt vmcnt(24)
	v_add_u32_e32 v187, 0x90000, v186
	v_lshrrev_b32_e32 v188, 1, v187
	v_pk_add_f32 v[232:233], v[52:53], v[232:233]
	v_pk_add_f32 v[234:235], v[54:55], v[234:235]
	global_store_dwordx4 v187, v[232:235], s[22:23]
	v_mul_f32_e32 v145, v233, v233
	v_fmac_f32_e32 v145, v232, v232
	v_mul_f32_e32 v147, v235, v235
	v_fmac_f32_e32 v147, v234, v234
	v_cvt_pk_bf16_f32 v148, v232, v233
	v_cvt_pk_bf16_f32 v149, v234, v235
	global_store_dwordx2 v188, v[148:149], s[28:29]
	v_add_f32_e32 v145, v145, v147
	v_pk_add_f32 v[236:237], v[48:49], v[236:237]
	v_pk_add_f32 v[238:239], v[50:51], v[238:239]
	global_store_dwordx4 v187, v[236:239], s[22:23] offset:64
	v_mul_f32_e32 v146, v237, v237
	v_fmac_f32_e32 v146, v236, v236
	v_mul_f32_e32 v147, v239, v239
	v_fmac_f32_e32 v147, v238, v238
	v_cvt_pk_bf16_f32 v150, v236, v237
	v_cvt_pk_bf16_f32 v151, v238, v239
	global_store_dwordx2 v188, v[150:151], s[28:29] offset:32
	v_add_f32_e32 v146, v146, v147
	v_add_f32_e32 v145, v145, v146
	v_pk_add_f32 v[240:241], v[28:29], v[240:241]
	v_pk_add_f32 v[242:243], v[30:31], v[242:243]
	global_store_dwordx4 v187, v[240:243], s[22:23] offset:512
	v_mul_f32_e32 v146, v241, v241
	v_fmac_f32_e32 v146, v240, v240
	v_mul_f32_e32 v147, v243, v243
	v_fmac_f32_e32 v147, v242, v242
	v_cvt_pk_bf16_f32 v148, v240, v241
	v_cvt_pk_bf16_f32 v149, v242, v243
	global_store_dwordx2 v188, v[148:149], s[28:29] offset:256
	v_add_f32_e32 v146, v146, v147
	v_add_f32_e32 v145, v145, v146
	v_pk_add_f32 v[244:245], v[20:21], v[244:245]
	v_pk_add_f32 v[246:247], v[22:23], v[246:247]
	global_store_dwordx4 v187, v[244:247], s[22:23] offset:576
	v_mul_f32_e32 v146, v245, v245
	v_fmac_f32_e32 v146, v244, v244
	v_mul_f32_e32 v147, v247, v247
	v_fmac_f32_e32 v147, v246, v246
	v_cvt_pk_bf16_f32 v150, v244, v245
	v_cvt_pk_bf16_f32 v151, v246, v247
	global_store_dwordx2 v188, v[150:151], s[28:29] offset:288
	v_add_f32_e32 v146, v146, v147
	v_add_f32_e32 v145, v145, v146
	ds_bpermute_b32 v130, v128, v145
	v_add_u32_e32 v131, 0x90, v144
	v_lshlrev_b32_e32 v131, 2, v131
	s_waitcnt lgkmcnt(0)
	v_add_f32_e32 v145, v145, v130
	ds_bpermute_b32 v130, v129, v145
	s_waitcnt lgkmcnt(0)
	v_add_f32_e32 v145, v145, v130
	s_and_saveexec_b64 s[2:3], s[38:39]
	global_atomic_add_f32 v131, v145, s[30:31]
	s_or_b64 exec, exec, s[2:3]
	s_waitcnt vmcnt(20)
; __device__ __forceinline__ unsigned pk2(float lo, float hi) { f32x2 v = {lo, hi}; bf16x2_t b = __builtin_convertvector(v, bf16x2_t); return __builtin_bit_cast(unsigned, b); }
;     __device__ __forceinline__ void operator()(const f32x4 (&acc)[2][2][4][2], const Unit& u, int wr, int wc, int fr, int fq) const {
;     ...
; #pragma unroll
;         for (int ai = 0; ai < 2; ++ai)
; #pragma unroll
;             for (int m = 0; m < 4; ++m) { const int row = u.pm * BM + ai * HALF + wr * 64 + m * 16 + fr; const size_t off = (size_t)row * DM + col0; float ss = 0.f;
; #pragma unroll
;                 for (int bj = 0; bj < 2; ++bj)
; #pragma unroll
;                     for (int n = 0; n < 2; ++n) { float* p = X + off + bj * HALF + n * 16; const f32x4 x = *(const f32x4*)(Xin + off + bj * HALF + n * 16) + acc[ai][bj][m][n]; *(f32x4*)p = x;
;                         ss += (x[0] * x[0] + x[1] * x[1]) + (x[2] * x[2] + x[3] * x[3]);
;                         if (XB) { u32x2 w; w.x = pk2(x[0], x[1]); w.y = pk2(x[2], x[3]); *(u32x2*)(XB + off + bj * HALF + n * 16) = w; } }
;                 if (rss_out) { ss += __shfl_xor(ss, 16); ss += __shfl_xor(ss, 32); if (fq == 0) atomicAdd(rss_out + row, ss); } }
	v_add_u32_e32 v187, 0xa0000, v186
	v_lshrrev_b32_e32 v188, 1, v187
	v_pk_add_f32 v[192:193], v[40:41], v[192:193]
	v_pk_add_f32 v[194:195], v[42:43], v[194:195]
	global_store_dwordx4 v187, v[192:195], s[22:23]
	v_mul_f32_e32 v145, v193, v193
	v_fmac_f32_e32 v145, v192, v192
	v_mul_f32_e32 v147, v195, v195
	v_fmac_f32_e32 v147, v194, v194
	v_cvt_pk_bf16_f32 v148, v192, v193
	v_cvt_pk_bf16_f32 v149, v194, v195
	global_store_dwordx2 v188, v[148:149], s[28:29]
	v_add_f32_e32 v145, v145, v147
	v_pk_add_f32 v[200:201], v[32:33], v[200:201]
	v_pk_add_f32 v[202:203], v[34:35], v[202:203]
	global_store_dwordx4 v187, v[200:203], s[22:23] offset:64
	v_mul_f32_e32 v146, v201, v201
	v_fmac_f32_e32 v146, v200, v200
	v_mul_f32_e32 v147, v203, v203
	v_fmac_f32_e32 v147, v202, v202
	v_cvt_pk_bf16_f32 v150, v200, v201
	v_cvt_pk_bf16_f32 v151, v202, v203
	global_store_dwordx2 v188, v[150:151], s[28:29] offset:32
	v_add_f32_e32 v146, v146, v147
	v_add_f32_e32 v145, v145, v146
	v_pk_add_f32 v[204:205], v[12:13], v[204:205]
	v_pk_add_f32 v[206:207], v[14:15], v[206:207]
	global_store_dwordx4 v187, v[204:207], s[22:23] offset:512
	v_mul_f32_e32 v146, v205, v205
	v_fmac_f32_e32 v146, v204, v204
	v_mul_f32_e32 v147, v207, v207
	v_fmac_f32_e32 v147, v206, v206
	v_cvt_pk_bf16_f32 v148, v204, v205
	v_cvt_pk_bf16_f32 v149, v206, v207
	global_store_dwordx2 v188, v[148:149], s[28:29] offset:256
	v_add_f32_e32 v146, v146, v147
	v_add_f32_e32 v145, v145, v146
	v_pk_add_f32 v[208:209], v[8:9], v[208:209]
	v_pk_add_f32 v[210:211], v[10:11], v[210:211]
	global_store_dwordx4 v187, v[208:211], s[22:23] offset:576
	v_mul_f32_e32 v146, v209, v209
	v_fmac_f32_e32 v146, v208, v208
	v_mul_f32_e32 v147, v211, v211
	v_fmac_f32_e32 v147, v210, v210
	v_cvt_pk_bf16_f32 v150, v208, v209
	v_cvt_pk_bf16_f32 v151, v210, v211
	global_store_dwordx2 v188, v[150:151], s[28:29] offset:288
	v_add_f32_e32 v146, v146, v147
	v_add_f32_e32 v145, v145, v146
	ds_bpermute_b32 v130, v128, v145
	v_add_u32_e32 v131, 0xa0, v144
	v_lshlrev_b32_e32 v131, 2, v131
	s_waitcnt lgkmcnt(0)
	v_add_f32_e32 v145, v145, v130
	ds_bpermute_b32 v130, v129, v145
	s_waitcnt lgkmcnt(0)
	v_add_f32_e32 v145, v145, v130
	s_and_saveexec_b64 s[2:3], s[38:39]
	global_atomic_add_f32 v131, v145, s[30:31]
	s_or_b64 exec, exec, s[2:3]
	s_waitcnt vmcnt(16)
	v_add_u32_e32 v187, 0xb0000, v186
	v_lshrrev_b32_e32 v188, 1, v187
	v_pk_add_f32 v[212:213], v[24:25], v[212:213]
	v_pk_add_f32 v[214:215], v[26:27], v[214:215]
	global_store_dwordx4 v187, v[212:215], s[22:23]
	v_mul_f32_e32 v145, v213, v213
	v_fmac_f32_e32 v145, v212, v212
	v_mul_f32_e32 v147, v215, v215
	v_fmac_f32_e32 v147, v214, v214
	v_cvt_pk_bf16_f32 v148, v212, v213
	v_cvt_pk_bf16_f32 v149, v214, v215
	global_store_dwordx2 v188, v[148:149], s[28:29]
	v_add_f32_e32 v145, v145, v147
	v_pk_add_f32 v[216:217], v[16:17], v[216:217]
	v_pk_add_f32 v[218:219], v[18:19], v[218:219]
	global_store_dwordx4 v187, v[216:219], s[22:23] offset:64
	v_mul_f32_e32 v146, v217, v217
	v_fmac_f32_e32 v146, v216, v216
	v_mul_f32_e32 v147, v219, v219
	v_fmac_f32_e32 v147, v218, v218
	v_cvt_pk_bf16_f32 v150, v216, v217
	v_cvt_pk_bf16_f32 v151, v218, v219
	global_store_dwordx2 v188, v[150:151], s[28:29] offset:32
	v_add_f32_e32 v146, v146, v147
	v_add_f32_e32 v145, v145, v146
	v_pk_add_f32 v[220:221], v[4:5], v[220:221]
	v_pk_add_f32 v[222:223], v[6:7], v[222:223]
	global_store_dwordx4 v187, v[220:223], s[22:23] offset:512
	v_mul_f32_e32 v146, v221, v221
	v_fmac_f32_e32 v146, v220, v220
	v_mul_f32_e32 v147, v223, v223
	v_fmac_f32_e32 v147, v222, v222
	v_cvt_pk_bf16_f32 v148, v220, v221
	v_cvt_pk_bf16_f32 v149, v222, v223
	global_store_dwordx2 v188, v[148:149], s[28:29] offset:256
	v_add_f32_e32 v146, v146, v147
	v_add_f32_e32 v145, v145, v146
	v_pk_add_f32 v[228:229], v[0:1], v[228:229]
	v_pk_add_f32 v[230:231], v[2:3], v[230:231]
	global_store_dwordx4 v187, v[228:231], s[22:23] offset:576
	v_mul_f32_e32 v146, v229, v229
	v_fmac_f32_e32 v146, v228, v228
	v_mul_f32_e32 v147, v231, v231
	v_fmac_f32_e32 v147, v230, v230
	v_cvt_pk_bf16_f32 v150, v228, v229
	v_cvt_pk_bf16_f32 v151, v230, v231
	global_store_dwordx2 v188, v[150:151], s[28:29] offset:288
	v_add_f32_e32 v146, v146, v147
	v_add_f32_e32 v145, v145, v146
	ds_bpermute_b32 v130, v128, v145
	v_add_u32_e32 v131, 0xb0, v144
	v_lshlrev_b32_e32 v131, 2, v131
	s_waitcnt lgkmcnt(0)
	v_add_f32_e32 v145, v145, v130
	ds_bpermute_b32 v130, v129, v145
	s_waitcnt lgkmcnt(0)
	v_add_f32_e32 v145, v145, v130
	s_and_saveexec_b64 s[2:3], s[38:39]
	global_atomic_add_f32 v131, v145, s[30:31]
	s_or_b64 exec, exec, s[2:3]
	s_branch .LBB0_823
; __device__ __forceinline__ unsigned pk2(float lo, float hi) { f32x2 v = {lo, hi}; bf16x2_t b = __builtin_convertvector(v, bf16x2_t); return __builtin_bit_cast(unsigned, b); }
;     __device__ __forceinline__ void operator()(const f32x4 (&acc)[2][2][4][2], const Unit& u, int wr, int wc, int fr, int fq) const {
;     ...
; #pragma unroll
;         for (int ai = 0; ai < 2; ++ai)
; #pragma unroll
;             for (int m = 0; m < 4; ++m) { const int row = u.pm * BM + ai * HALF + wr * 64 + m * 16 + fr; const size_t off = (size_t)row * DM + col0; float ss = 0.f;
; #pragma unroll
;                 for (int bj = 0; bj < 2; ++bj)
; #pragma unroll
;                     for (int n = 0; n < 2; ++n) { float* p = X + off + bj * HALF + n * 16; const f32x4 x = *(const f32x4*)(Xin + off + bj * HALF + n * 16) + acc[ai][bj][m][n]; *(f32x4*)p = x;
;                         ss += (x[0] * x[0] + x[1] * x[1]) + (x[2] * x[2] + x[3] * x[3]);
;                         if (XB) { u32x2 w; w.x = pk2(x[0], x[1]); w.y = pk2(x[2], x[3]); *(u32x2*)(XB + off + bj * HALF + n * 16) = w; } }
.Lp6_plain:
	s_lshl_b32 s37, s24, 8
	v_add_u32_e32 v144, s37, v170
	v_lshl_add_u32 v186, v144, 10, v142
	v_lshlrev_b32_e32 v186, 2, v186
	global_load_dwordx4 v[192:195], v186, s[14:15]
	global_load_dwordx4 v[200:203], v186, s[14:15] offset:64
	global_load_dwordx4 v[204:207], v186, s[14:15] offset:512
	global_load_dwordx4 v[208:211], v186, s[14:15] offset:576
	v_add_u32_e32 v187, 0x10000, v186
	global_load_dwordx4 v[212:215], v187, s[14:15]
	global_load_dwordx4 v[216:219], v187, s[14:15] offset:64
	global_load_dwordx4 v[220:223], v187, s[14:15] offset:512
	global_load_dwordx4 v[228:231], v187, s[14:15] offset:576
	v_add_u32_e32 v187, 0x20000, v186
	global_load_dwordx4 v[232:235], v187, s[14:15]
	global_load_dwordx4 v[236:239], v187, s[14:15] offset:64
	global_load_dwordx4 v[240:243], v187, s[14:15] offset:512
	global_load_dwordx4 v[244:247], v187, s[14:15] offset:576
	s_waitcnt vmcnt(8)
	v_pk_add_f32 v[192:193], v[124:125], v[192:193]
	v_pk_add_f32 v[194:195], v[126:127], v[194:195]
	global_store_dwordx4 v186, v[192:195], s[22:23]
	v_pk_add_f32 v[200:201], v[120:121], v[200:201]
	v_pk_add_f32 v[202:203], v[122:123], v[202:203]
	global_store_dwordx4 v186, v[200:203], s[22:23] offset:64
	v_pk_add_f32 v[204:205], v[108:109], v[204:205]
	v_pk_add_f32 v[206:207], v[110:111], v[206:207]
	global_store_dwordx4 v186, v[204:207], s[22:23] offset:512
	v_pk_add_f32 v[208:209], v[100:101], v[208:209]
	v_pk_add_f32 v[210:211], v[102:103], v[210:211]
	global_store_dwordx4 v186, v[208:211], s[22:23] offset:576
	v_add_u32_e32 v187, 0x30000, v186
	global_load_dwordx4 v[192:195], v187, s[14:15]
	global_load_dwordx4 v[200:203], v187, s[14:15] offset:64
	global_load_dwordx4 v[204:207], v187, s[14:15] offset:512
	global_load_dwordx4 v[208:211], v187, s[14:15] offset:576
	s_waitcnt vmcnt(12)
	v_add_u32_e32 v187, 0x10000, v186
	v_pk_add_f32 v[212:213], v[116:117], v[212:213]
	v_pk_add_f32 v[214:215], v[118:119], v[214:215]
	global_store_dwordx4 v187, v[212:215], s[22:23]
	v_pk_add_f32 v[216:217], v[112:113], v[216:217]
	v_pk_add_f32 v[218:219], v[114:115], v[218:219]
	global_store_dwordx4 v187, v[216:219], s[22:23] offset:64
	v_pk_add_f32 v[220:221], v[92:93], v[220:221]
	v_pk_add_f32 v[222:223], v[94:95], v[222:223]
	global_store_dwordx4 v187, v[220:223], s[22:23] offset:512
	v_pk_add_f32 v[228:229], v[84:85], v[228:229]
	v_pk_add_f32 v[230:231], v[86:87], v[230:231]
	global_store_dwordx4 v187, v[228:231], s[22:23] offset:576
	v_add_u32_e32 v187, 0x80000, v186
	global_load_dwordx4 v[212:215], v187, s[14:15]
	global_load_dwordx4 v[216:219], v187, s[14:15] offset:64
	global_load_dwordx4 v[220:223], v187, s[14:15] offset:512
	global_load_dwordx4 v[228:231], v187, s[14:15] offset:576
	s_waitcnt vmcnt(16)
	v_add_u32_e32 v187, 0x20000, v186
	v_pk_add_f32 v[232:233], v[104:105], v[232:233]
	v_pk_add_f32 v[234:235], v[106:107], v[234:235]
	global_store_dwordx4 v187, v[232:235], s[22:23]
	v_pk_add_f32 v[236:237], v[96:97], v[236:237]
	v_pk_add_f32 v[238:239], v[98:99], v[238:239]
	global_store_dwordx4 v187, v[236:239], s[22:23] offset:64
	v_pk_add_f32 v[240:241], v[76:77], v[240:241]
	v_pk_add_f32 v[242:243], v[78:79], v[242:243]
	global_store_dwordx4 v187, v[240:243], s[22:23] offset:512
	v_pk_add_f32 v[244:245], v[72:73], v[244:245]
	v_pk_add_f32 v[246:247], v[74:75], v[246:247]
	global_store_dwordx4 v187, v[244:247], s[22:23] offset:576
	v_add_u32_e32 v187, 0x90000, v186
	global_load_dwordx4 v[232:235], v187, s[14:15]
	global_load_dwordx4 v[236:239], v187, s[14:15] offset:64
	global_load_dwordx4 v[240:243], v187, s[14:15] offset:512
	global_load_dwordx4 v[244:247], v187, s[14:15] offset:576
	s_waitcnt vmcnt(16)
; __device__ __forceinline__ unsigned pk2(float lo, float hi) { f32x2 v = {lo, hi}; bf16x2_t b = __builtin_convertvector(v, bf16x2_t); return __builtin_bit_cast(unsigned, b); }
;     __device__ __forceinline__ void operator()(const f32x4 (&acc)[2][2][4][2], const Unit& u, int wr, int wc, int fr, int fq) const {
;     ...
; #pragma unroll
;         for (int ai = 0; ai < 2; ++ai)
; #pragma unroll
;             for (int m = 0; m < 4; ++m) { const int row = u.pm * BM + ai * HALF + wr * 64 + m * 16 + fr; const size_t off = (size_t)row * DM + col0; float ss = 0.f;
; #pragma unroll
;                 for (int bj = 0; bj < 2; ++bj)
; #pragma unroll
;                     for (int n = 0; n < 2; ++n) { float* p = X + off + bj * HALF + n * 16; const f32x4 x = *(const f32x4*)(Xin + off + bj * HALF + n * 16) + acc[ai][bj][m][n]; *(f32x4*)p = x;
;                         ss += (x[0] * x[0] + x[1] * x[1]) + (x[2] * x[2] + x[3] * x[3]);
;                         if (XB) { u32x2 w; w.x = pk2(x[0], x[1]); w.y = pk2(x[2], x[3]); *(u32x2*)(XB + off + bj * HALF + n * 16) = w; } }
	v_add_u32_e32 v187, 0x30000, v186
	v_pk_add_f32 v[192:193], v[88:89], v[192:193]
	v_pk_add_f32 v[194:195], v[90:91], v[194:195]
	global_store_dwordx4 v187, v[192:195], s[22:23]
	v_pk_add_f32 v[200:201], v[80:81], v[200:201]
	v_pk_add_f32 v[202:203], v[82:83], v[202:203]
	global_store_dwordx4 v187, v[200:203], s[22:23] offset:64
	v_pk_add_f32 v[204:205], v[68:69], v[204:205]
	v_pk_add_f32 v[206:207], v[70:71], v[206:207]
	global_store_dwordx4 v187, v[204:207], s[22:23] offset:512
	v_pk_add_f32 v[208:209], v[64:65], v[208:209]
	v_pk_add_f32 v[210:211], v[66:67], v[210:211]
	global_store_dwordx4 v187, v[208:211], s[22:23] offset:576
	v_add_u32_e32 v187, 0xa0000, v186
	global_load_dwordx4 v[192:195], v187, s[14:15]
	global_load_dwordx4 v[200:203], v187, s[14:15] offset:64
	global_load_dwordx4 v[204:207], v187, s[14:15] offset:512
	global_load_dwordx4 v[208:211], v187, s[14:15] offset:576
	s_waitcnt vmcnt(16)
	v_add_u32_e32 v187, 0x80000, v186
	v_pk_add_f32 v[212:213], v[60:61], v[212:213]
	v_pk_add_f32 v[214:215], v[62:63], v[214:215]
	global_store_dwordx4 v187, v[212:215], s[22:23]
	v_pk_add_f32 v[216:217], v[56:57], v[216:217]
	v_pk_add_f32 v[218:219], v[58:59], v[218:219]
	global_store_dwordx4 v187, v[216:219], s[22:23] offset:64
	v_pk_add_f32 v[220:221], v[44:45], v[220:221]
	v_pk_add_f32 v[222:223], v[46:47], v[222:223]
	global_store_dwordx4 v187, v[220:223], s[22:23] offset:512
	v_pk_add_f32 v[228:229], v[36:37], v[228:229]
	v_pk_add_f32 v[230:231], v[38:39], v[230:231]
	global_store_dwordx4 v187, v[228:231], s[22:23] offset:576
	v_add_u32_e32 v187, 0xb0000, v186
	global_load_dwordx4 v[212:215], v187, s[14:15]
	global_load_dwordx4 v[216:219], v187, s[14:15] offset:64
	global_load_dwordx4 v[220:223], v187, s[14:15] offset:512
	global_load_dwordx4 v[228:231], v187, s[14:15] offset:576
	s_waitcnt vmcnt(16)
	v_add_u32_e32 v187, 0x90000, v186
	v_pk_add_f32 v[232:233], v[52:53], v[232:233]
	v_pk_add_f32 v[234:235], v[54:55], v[234:235]
	global_store_dwordx4 v187, v[232:235], s[22:23]
	v_pk_add_f32 v[236:237], v[48:49], v[236:237]
	v_pk_add_f32 v[238:239], v[50:51], v[238:239]
	global_store_dwordx4 v187, v[236:239], s[22:23] offset:64
	v_pk_add_f32 v[240:241], v[28:29], v[240:241]
	v_pk_add_f32 v[242:243], v[30:31], v[242:243]
	global_store_dwordx4 v187, v[240:243], s[22:23] offset:512
	v_pk_add_f32 v[244:245], v[20:21], v[244:245]
	v_pk_add_f32 v[246:247], v[22:23], v[246:247]
	global_store_dwordx4 v187, v[244:247], s[22:23] offset:576
	s_waitcnt vmcnt(12)
	v_add_u32_e32 v187, 0xa0000, v186
	v_pk_add_f32 v[192:193], v[40:41], v[192:193]
	v_pk_add_f32 v[194:195], v[42:43], v[194:195]
	global_store_dwordx4 v187, v[192:195], s[22:23]
	v_pk_add_f32 v[200:201], v[32:33], v[200:201]
	v_pk_add_f32 v[202:203], v[34:35], v[202:203]
	global_store_dwordx4 v187, v[200:203], s[22:23] offset:64
	v_pk_add_f32 v[204:205], v[12:13], v[204:205]
	v_pk_add_f32 v[206:207], v[14:15], v[206:207]
	global_store_dwordx4 v187, v[204:207], s[22:23] offset:512
	v_pk_add_f32 v[208:209], v[8:9], v[208:209]
	v_pk_add_f32 v[210:211], v[10:11], v[210:211]
	global_store_dwordx4 v187, v[208:211], s[22:23] offset:576
	s_waitcnt vmcnt(8)
	v_add_u32_e32 v187, 0xb0000, v186
	v_pk_add_f32 v[212:213], v[24:25], v[212:213]
	v_pk_add_f32 v[214:215], v[26:27], v[214:215]
	global_store_dwordx4 v187, v[212:215], s[22:23]
	v_pk_add_f32 v[216:217], v[16:17], v[216:217]
	v_pk_add_f32 v[218:219], v[18:19], v[218:219]
	global_store_dwordx4 v187, v[216:219], s[22:23] offset:64
	v_pk_add_f32 v[220:221], v[4:5], v[220:221]
	v_pk_add_f32 v[222:223], v[6:7], v[222:223]
	global_store_dwordx4 v187, v[220:223], s[22:23] offset:512
	v_pk_add_f32 v[228:229], v[0:1], v[228:229]
	v_pk_add_f32 v[230:231], v[2:3], v[230:231]
	global_store_dwordx4 v187, v[228:231], s[22:23] offset:576
	s_branch .LBB0_823

; #define OPQ_TID() int tid = threadIdx.x; asm volatile("" : "+v"(tid)); const int lane = tid & 63, wave = __builtin_amdgcn_readfirstlane(tid >> 6), gw = blockIdx.x * NWAVES + wave; (void)lane; (void)gw
; __device__ __forceinline__ void sample_combine(const float* XinS  , float* X, const float* slab, int S, bf16_t* XB, float* rss, int gw, int NGW, int lane) {
;     for (int r = gw; r < TS; r += NGW) { const size_t row = (size_t)TP + r; float ss = 0.f;
; #pragma unroll
;         for (int j = 0; j < 4; ++j) { const int c = 4 * lane + 256 * j; f32x4 v = *(const f32x4*)(XinS + (size_t)r * DM + c);
;             for (int s = 0; s < S; ++s) v += *(const f32x4*)(slab + ((size_t)s * TS + r) * DM + c);
; __global__ void __launch_bounds__(NWAVES * 64, 2) fwd_mega(Args args) {
;     ...
;         if (IN(pb + 6) && EN_P6) {
;             OPQ_TID();
;             unsigned char* ws = KWS;
;             sample_combine((const float*)KOUT + (size_t)TP * DM, KOUT, (const float*)(ws + WS_KS + (size_t)l * KS_LAYER), SPLIT6, (l + 1 < DEPTH) ? (bf16_t*)(ws + WS_XB) : nullptr, (l + 1 < DEPTH) ? (float*)(ws + WS_RSS) + (size_t)(2 * l + 2) * MT : nullptr, gw, NGW, lane);
.LBB0_932:
	s_cmp_le_i32 s78, s4
	s_cselect_b64 s[2:3], -1, 0
	s_cmp_lt_i32 s4, s79
	s_cselect_b64 s[10:11], -1, 0
	s_and_b64 s[2:3], s[2:3], s[10:11]
	s_andn2_b64 vcc, exec, s[2:3]
	s_cbranch_vccnz .LBB0_131
	v_mov_b32_e32 v0, v173
	s_waitcnt lgkmcnt(0)
	s_load_dwordx2 s[22:23], s[0:1], 0x98
	s_load_dwordx2 s[24:25], s[0:1], 0x90
	s_load_dwordx2 s[26:27], s[0:1], 0x90
	v_readfirstlane_b32 s2, v0
	s_ashr_i32 s2, s2, 6
	s_mul_i32 s2, s2, s33
	s_add_i32 s2, s2, s76
	s_cmpk_gt_i32 s2, 0x1ff
	s_cbranch_scc1 .LBB0_946
	s_waitcnt lgkmcnt(0)
	s_add_u32 s3, s22, 0x3400000
	v_readlane_b32 s14, v255, 10
	s_addc_u32 s4, s23, 0
	v_readlane_b32 s15, v255, 11
	s_and_b64 s[10:11], s[14:15], exec
	s_cselect_b32 s30, s4, 0
	s_mul_i32 s4, s62, 0x8400
	s_cselect_b32 s31, s3, 0
	s_lshl_b64 s[10:11], s[4:5], 2
	s_add_u32 s3, s22, s10
	s_addc_u32 s4, s23, s11
	s_add_u32 s3, s3, 0x5521000
	s_addc_u32 s4, s4, 0
	s_and_b64 s[10:11], s[14:15], exec
	s_cselect_b32 s11, s4, 0
	s_cselect_b32 s10, s3, 0
	v_and_b32_e32 v0, 63, v0
	v_and_b32_e32 v1, 64, v191
	s_cmp_lg_u64 s[10:11], 0
	v_add_u32_e32 v1, 64, v1
	s_cselect_b64 s[14:15], -1, 0
	v_cmp_eq_u32_e32 vcc, 0, v0
	v_xor_b32_e32 v2, 1, v191
	s_and_b64 s[14:15], vcc, s[14:15]
	v_cmp_lt_i32_e32 vcc, v2, v1
	s_ashr_i32 s3, s2, 31
	s_lshl_b64 s[28:29], s[2:3], 12
	v_cndmask_b32_e32 v2, v191, v2, vcc
	v_lshlrev_b32_e32 v20, 2, v2
	v_xor_b32_e32 v2, 2, v191
	v_cmp_lt_i32_e32 vcc, v2, v1
	s_add_u32 s18, s24, s28
	s_mov_b32 s4, 0
	v_cndmask_b32_e32 v2, v191, v2, vcc
	v_lshlrev_b32_e32 v21, 2, v2
	v_xor_b32_e32 v2, 4, v191
	v_cmp_lt_i32_e32 vcc, v2, v1
	s_addc_u32 s19, s25, s29
	s_add_u32 s4, s4, s28
	v_cndmask_b32_e32 v2, v191, v2, vcc
	v_lshlrev_b32_e32 v22, 2, v2
	v_xor_b32_e32 v2, 8, v191
	v_cmp_lt_i32_e32 vcc, v2, v1
	s_addc_u32 s24, 0, s29
	s_add_u32 s22, s22, s4
	v_cndmask_b32_e32 v2, v191, v2, vcc
	v_lshlrev_b32_e32 v23, 2, v2
	v_xor_b32_e32 v2, 16, v191
	v_cmp_lt_i32_e32 vcc, v2, v1
	s_addc_u32 s23, s23, s24
	s_lshl_b64 s[24:25], s[2:3], 11
	v_cndmask_b32_e32 v2, v191, v2, vcc
	v_lshlrev_b32_e32 v24, 2, v2
	v_xor_b32_e32 v2, 32, v191
	v_cmp_lt_i32_e32 vcc, v2, v1
	s_add_u32 s24, s31, s24
	v_lshlrev_b32_e32 v152, 4, v0
	v_cndmask_b32_e32 v1, v191, v2, vcc
	v_lshlrev_b32_e32 v25, 2, v1
	v_lshlrev_b32_e32 v0, 3, v0
	v_mov_b32_e32 v1, v153
	s_addc_u32 s25, s30, s25
	v_lshl_add_u64 v[0:1], s[24:25], 0, v[0:1]
	s_mov_b64 s[24:25], 0x2000600
	v_lshl_add_u64 v[16:17], v[0:1], 0, s[24:25]
	s_lshl_b64 s[24:25], s[2:3], 2
	s_add_u32 s3, s10, s24
	s_addc_u32 s4, s11, s25
	s_add_u32 s24, s3, 0x10000
	s_addc_u32 s25, s4, 0
	s_add_u32 s26, s26, s28
	s_addc_u32 s27, s27, s29
	s_branch .LBB0_936

; __device__ __forceinline__ unsigned pk2(float lo, float hi) { f32x2 v = {lo, hi}; bf16x2_t b = __builtin_convertvector(v, bf16x2_t); return __builtin_bit_cast(unsigned, b); }
; __device__ __forceinline__ void sample_combine(const float* XinS  , float* X, const float* slab, int S, bf16_t* XB, float* rss, int gw, int NGW, int lane) {
;     for (int r = gw; r < TS; r += NGW) { const size_t row = (size_t)TP + r; float ss = 0.f;
; #pragma unroll
;         for (int j = 0; j < 4; ++j) { const int c = 4 * lane + 256 * j; f32x4 v = *(const f32x4*)(XinS + (size_t)r * DM + c);
;             for (int s = 0; s < S; ++s) v += *(const f32x4*)(slab + ((size_t)s * TS + r) * DM + c);
;             *(f32x4*)(X + row * DM + c) = v; ss += (v[0] * v[0] + v[1] * v[1]) + (v[2] * v[2] + v[3] * v[3]);
;             if (XB) { u32x2 w; w.x = pk2(v[0], v[1]); w.y = pk2(v[2], v[3]); *(u32x2*)(XB + row * DM + c) = w; } }
.LBB0_936:
	s_waitcnt lgkmcnt(0)
	s_add_u32 s10, s18, 0x4000000
	s_addc_u32 s11, s19, 0
	global_load_dwordx4 v[32:35], v152, s[10:11]
	global_load_dwordx4 v[36:39], v152, s[10:11] offset:1024
	global_load_dwordx4 v[40:43], v152, s[10:11] offset:2048
	global_load_dwordx4 v[44:47], v152, s[10:11] offset:3072
	s_add_u32 s10, s22, 0x5900000
	s_addc_u32 s11, s23, 0
	global_load_dwordx4 v[48:51], v152, s[10:11]
	global_load_dwordx4 v[52:55], v152, s[10:11] offset:1024
	global_load_dwordx4 v[56:59], v152, s[10:11] offset:2048
	global_load_dwordx4 v[60:63], v152, s[10:11] offset:3072
	s_add_u32 s10, s10, 0x200000
	s_addc_u32 s11, s11, 0
	global_load_dwordx4 v[64:67], v152, s[10:11]
	global_load_dwordx4 v[68:71], v152, s[10:11] offset:1024
	global_load_dwordx4 v[72:75], v152, s[10:11] offset:2048
	global_load_dwordx4 v[76:79], v152, s[10:11] offset:3072
	s_add_u32 s10, s10, 0x200000
	s_addc_u32 s11, s11, 0
	global_load_dwordx4 v[80:83], v152, s[10:11]
	global_load_dwordx4 v[84:87], v152, s[10:11] offset:1024
	global_load_dwordx4 v[88:91], v152, s[10:11] offset:2048
	global_load_dwordx4 v[92:95], v152, s[10:11] offset:3072
	s_add_u32 s10, s10, 0x200000
	s_addc_u32 s11, s11, 0
	global_load_dwordx4 v[96:99], v152, s[10:11]
	global_load_dwordx4 v[100:103], v152, s[10:11] offset:1024
	global_load_dwordx4 v[104:107], v152, s[10:11] offset:2048
	global_load_dwordx4 v[108:111], v152, s[10:11] offset:3072
	s_add_u32 s10, s10, 0x200000
	s_addc_u32 s11, s11, 0
	s_waitcnt vmcnt(0)
	v_pk_add_f32 v[32:33], v[32:33], v[48:49]
	v_pk_add_f32 v[34:35], v[34:35], v[50:51]
	v_pk_add_f32 v[36:37], v[36:37], v[52:53]
	v_pk_add_f32 v[38:39], v[38:39], v[54:55]
	v_pk_add_f32 v[40:41], v[40:41], v[56:57]
	v_pk_add_f32 v[42:43], v[42:43], v[58:59]
	v_pk_add_f32 v[44:45], v[44:45], v[60:61]
	v_pk_add_f32 v[46:47], v[46:47], v[62:63]
	v_pk_add_f32 v[32:33], v[32:33], v[64:65]
	v_pk_add_f32 v[34:35], v[34:35], v[66:67]
	v_pk_add_f32 v[36:37], v[36:37], v[68:69]
	v_pk_add_f32 v[38:39], v[38:39], v[70:71]
	v_pk_add_f32 v[40:41], v[40:41], v[72:73]
	v_pk_add_f32 v[42:43], v[42:43], v[74:75]
	v_pk_add_f32 v[44:45], v[44:45], v[76:77]
	v_pk_add_f32 v[46:47], v[46:47], v[78:79]
	v_pk_add_f32 v[32:33], v[32:33], v[80:81]
	v_pk_add_f32 v[34:35], v[34:35], v[82:83]
	v_pk_add_f32 v[36:37], v[36:37], v[84:85]
	v_pk_add_f32 v[38:39], v[38:39], v[86:87]
	v_pk_add_f32 v[40:41], v[40:41], v[88:89]
	v_pk_add_f32 v[42:43], v[42:43], v[90:91]
	v_pk_add_f32 v[44:45], v[44:45], v[92:93]
	v_pk_add_f32 v[46:47], v[46:47], v[94:95]
	v_pk_add_f32 v[32:33], v[32:33], v[96:97]
	v_pk_add_f32 v[34:35], v[34:35], v[98:99]
	v_pk_add_f32 v[36:37], v[36:37], v[100:101]
	v_pk_add_f32 v[38:39], v[38:39], v[102:103]
	v_pk_add_f32 v[40:41], v[40:41], v[104:105]
	v_pk_add_f32 v[42:43], v[42:43], v[106:107]
	v_pk_add_f32 v[44:45], v[44:45], v[108:109]
	v_pk_add_f32 v[46:47], v[46:47], v[110:111]
	global_load_dwordx4 v[48:51], v152, s[10:11]
	global_load_dwordx4 v[52:55], v152, s[10:11] offset:1024
	global_load_dwordx4 v[56:59], v152, s[10:11] offset:2048
	global_load_dwordx4 v[60:63], v152, s[10:11] offset:3072
	s_add_u32 s10, s10, 0x200000
	s_addc_u32 s11, s11, 0
	global_load_dwordx4 v[64:67], v152, s[10:11]
	global_load_dwordx4 v[68:71], v152, s[10:11] offset:1024
	global_load_dwordx4 v[72:75], v152, s[10:11] offset:2048
	global_load_dwordx4 v[76:79], v152, s[10:11] offset:3072
	s_add_u32 s10, s10, 0x200000
	s_addc_u32 s11, s11, 0
	global_load_dwordx4 v[80:83], v152, s[10:11]
	global_load_dwordx4 v[84:87], v152, s[10:11] offset:1024
	global_load_dwordx4 v[88:91], v152, s[10:11] offset:2048
	global_load_dwordx4 v[92:95], v152, s[10:11] offset:3072
	s_add_u32 s10, s10, 0x200000
	s_addc_u32 s11, s11, 0
	global_load_dwordx4 v[96:99], v152, s[10:11]
	global_load_dwordx4 v[100:103], v152, s[10:11] offset:1024
	global_load_dwordx4 v[104:107], v152, s[10:11] offset:2048
	global_load_dwordx4 v[108:111], v152, s[10:11] offset:3072
	s_add_u32 s10, s10, 0x200000
	s_addc_u32 s11, s11, 0
	s_waitcnt vmcnt(0)
	v_pk_add_f32 v[32:33], v[32:33], v[48:49]
	v_pk_add_f32 v[34:35], v[34:35], v[50:51]
	v_pk_add_f32 v[36:37], v[36:37], v[52:53]
	v_pk_add_f32 v[38:39], v[38:39], v[54:55]
	v_pk_add_f32 v[40:41], v[40:41], v[56:57]
	v_pk_add_f32 v[42:43], v[42:43], v[58:59]
	v_pk_add_f32 v[44:45], v[44:45], v[60:61]
	v_pk_add_f32 v[46:47], v[46:47], v[62:63]
	v_pk_add_f32 v[32:33], v[32:33], v[64:65]
	v_pk_add_f32 v[34:35], v[34:35], v[66:67]
	v_pk_add_f32 v[36:37], v[36:37], v[68:69]
	v_pk_add_f32 v[38:39], v[38:39], v[70:71]
	v_pk_add_f32 v[40:41], v[40:41], v[72:73]
	v_pk_add_f32 v[42:43], v[42:43], v[74:75]
	v_pk_add_f32 v[44:45], v[44:45], v[76:77]
	v_pk_add_f32 v[46:47], v[46:47], v[78:79]
	v_pk_add_f32 v[32:33], v[32:33], v[80:81]
	v_pk_add_f32 v[34:35], v[34:35], v[82:83]
	v_pk_add_f32 v[36:37], v[36:37], v[84:85]
	v_pk_add_f32 v[38:39], v[38:39], v[86:87]
	v_pk_add_f32 v[40:41], v[40:41], v[88:89]
	v_pk_add_f32 v[42:43], v[42:43], v[90:91]
	v_pk_add_f32 v[44:45], v[44:45], v[92:93]
	v_pk_add_f32 v[46:47], v[46:47], v[94:95]
	v_pk_add_f32 v[32:33], v[32:33], v[96:97]
	v_pk_add_f32 v[34:35], v[34:35], v[98:99]
	v_pk_add_f32 v[36:37], v[36:37], v[100:101]
	v_pk_add_f32 v[38:39], v[38:39], v[102:103]
	v_pk_add_f32 v[40:41], v[40:41], v[104:105]
	v_pk_add_f32 v[42:43], v[42:43], v[106:107]
	v_pk_add_f32 v[44:45], v[44:45], v[108:109]
	v_pk_add_f32 v[46:47], v[46:47], v[110:111]
	global_load_dwordx4 v[48:51], v152, s[10:11]
	global_load_dwordx4 v[52:55], v152, s[10:11] offset:1024
	global_load_dwordx4 v[56:59], v152, s[10:11] offset:2048
	global_load_dwordx4 v[60:63], v152, s[10:11] offset:3072
	s_add_u32 s10, s10, 0x200000
	s_addc_u32 s11, s11, 0
	global_load_dwordx4 v[64:67], v152, s[10:11]
	global_load_dwordx4 v[68:71], v152, s[10:11] offset:1024
	global_load_dwordx4 v[72:75], v152, s[10:11] offset:2048
	global_load_dwordx4 v[76:79], v152, s[10:11] offset:3072
	s_add_u32 s10, s10, 0x200000
	s_addc_u32 s11, s11, 0
	global_load_dwordx4 v[80:83], v152, s[10:11]
	global_load_dwordx4 v[84:87], v152, s[10:11] offset:1024
	global_load_dwordx4 v[88:91], v152, s[10:11] offset:2048
	global_load_dwordx4 v[92:95], v152, s[10:11] offset:3072
	s_add_u32 s10, s10, 0x200000
	s_addc_u32 s11, s11, 0
	global_load_dwordx4 v[96:99], v152, s[10:11]
	global_load_dwordx4 v[100:103], v152, s[10:11] offset:1024
	global_load_dwordx4 v[104:107], v152, s[10:11] offset:2048
	global_load_dwordx4 v[108:111], v152, s[10:11] offset:3072
	s_add_u32 s10, s10, 0x200000
	s_addc_u32 s11, s11, 0
	s_waitcnt vmcnt(0)
; __device__ __forceinline__ unsigned pk2(float lo, float hi) { f32x2 v = {lo, hi}; bf16x2_t b = __builtin_convertvector(v, bf16x2_t); return __builtin_bit_cast(unsigned, b); }
; __device__ __forceinline__ void sample_combine(const float* XinS  , float* X, const float* slab, int S, bf16_t* XB, float* rss, int gw, int NGW, int lane) {
;     for (int r = gw; r < TS; r += NGW) { const size_t row = (size_t)TP + r; float ss = 0.f;
; #pragma unroll
;         for (int j = 0; j < 4; ++j) { const int c = 4 * lane + 256 * j; f32x4 v = *(const f32x4*)(XinS + (size_t)r * DM + c);
;             for (int s = 0; s < S; ++s) v += *(const f32x4*)(slab + ((size_t)s * TS + r) * DM + c);
;             *(f32x4*)(X + row * DM + c) = v; ss += (v[0] * v[0] + v[1] * v[1]) + (v[2] * v[2] + v[3] * v[3]);
;             if (XB) { u32x2 w; w.x = pk2(v[0], v[1]); w.y = pk2(v[2], v[3]); *(u32x2*)(XB + row * DM + c) = w; } }
; #pragma unroll
;         for (int ofs = 1; ofs < 64; ofs <<= 1) ss += __shfl_xor(ss, ofs);
;         if (rss && lane == 0) rss[row] = ss; }
	v_pk_add_f32 v[32:33], v[32:33], v[48:49]
	v_pk_add_f32 v[34:35], v[34:35], v[50:51]
	v_pk_add_f32 v[36:37], v[36:37], v[52:53]
	v_pk_add_f32 v[38:39], v[38:39], v[54:55]
	v_pk_add_f32 v[40:41], v[40:41], v[56:57]
	v_pk_add_f32 v[42:43], v[42:43], v[58:59]
	v_pk_add_f32 v[44:45], v[44:45], v[60:61]
	v_pk_add_f32 v[46:47], v[46:47], v[62:63]
	v_pk_add_f32 v[32:33], v[32:33], v[64:65]
	v_pk_add_f32 v[34:35], v[34:35], v[66:67]
	v_pk_add_f32 v[36:37], v[36:37], v[68:69]
	v_pk_add_f32 v[38:39], v[38:39], v[70:71]
	v_pk_add_f32 v[40:41], v[40:41], v[72:73]
	v_pk_add_f32 v[42:43], v[42:43], v[74:75]
	v_pk_add_f32 v[44:45], v[44:45], v[76:77]
	v_pk_add_f32 v[46:47], v[46:47], v[78:79]
	v_pk_add_f32 v[32:33], v[32:33], v[80:81]
	v_pk_add_f32 v[34:35], v[34:35], v[82:83]
	v_pk_add_f32 v[36:37], v[36:37], v[84:85]
	v_pk_add_f32 v[38:39], v[38:39], v[86:87]
	v_pk_add_f32 v[40:41], v[40:41], v[88:89]
	v_pk_add_f32 v[42:43], v[42:43], v[90:91]
	v_pk_add_f32 v[44:45], v[44:45], v[92:93]
	v_pk_add_f32 v[46:47], v[46:47], v[94:95]
	v_pk_add_f32 v[32:33], v[32:33], v[96:97]
	v_pk_add_f32 v[34:35], v[34:35], v[98:99]
	v_pk_add_f32 v[36:37], v[36:37], v[100:101]
	v_pk_add_f32 v[38:39], v[38:39], v[102:103]
	v_pk_add_f32 v[40:41], v[40:41], v[104:105]
	v_pk_add_f32 v[42:43], v[42:43], v[106:107]
	v_pk_add_f32 v[44:45], v[44:45], v[108:109]
	v_pk_add_f32 v[46:47], v[46:47], v[110:111]
	global_load_dwordx4 v[48:51], v152, s[10:11]
	global_load_dwordx4 v[52:55], v152, s[10:11] offset:1024
	global_load_dwordx4 v[56:59], v152, s[10:11] offset:2048
	global_load_dwordx4 v[60:63], v152, s[10:11] offset:3072
	s_add_u32 s10, s10, 0x200000
	s_addc_u32 s11, s11, 0
	global_load_dwordx4 v[64:67], v152, s[10:11]
	global_load_dwordx4 v[68:71], v152, s[10:11] offset:1024
	global_load_dwordx4 v[72:75], v152, s[10:11] offset:2048
	global_load_dwordx4 v[76:79], v152, s[10:11] offset:3072
	s_add_u32 s10, s10, 0x200000
	s_addc_u32 s11, s11, 0
	global_load_dwordx4 v[80:83], v152, s[10:11]
	global_load_dwordx4 v[84:87], v152, s[10:11] offset:1024
	global_load_dwordx4 v[88:91], v152, s[10:11] offset:2048
	global_load_dwordx4 v[92:95], v152, s[10:11] offset:3072
	s_add_u32 s10, s10, 0x200000
	s_addc_u32 s11, s11, 0
	global_load_dwordx4 v[96:99], v152, s[10:11]
	global_load_dwordx4 v[100:103], v152, s[10:11] offset:1024
	global_load_dwordx4 v[104:107], v152, s[10:11] offset:2048
	global_load_dwordx4 v[108:111], v152, s[10:11] offset:3072
	s_add_u32 s10, s10, 0x200000
	s_addc_u32 s11, s11, 0
	s_waitcnt vmcnt(0)
	v_pk_add_f32 v[32:33], v[32:33], v[48:49]
	v_pk_add_f32 v[34:35], v[34:35], v[50:51]
	v_pk_add_f32 v[36:37], v[36:37], v[52:53]
	v_pk_add_f32 v[38:39], v[38:39], v[54:55]
	v_pk_add_f32 v[40:41], v[40:41], v[56:57]
	v_pk_add_f32 v[42:43], v[42:43], v[58:59]
	v_pk_add_f32 v[44:45], v[44:45], v[60:61]
	v_pk_add_f32 v[46:47], v[46:47], v[62:63]
	v_pk_add_f32 v[32:33], v[32:33], v[64:65]
	v_pk_add_f32 v[34:35], v[34:35], v[66:67]
	v_pk_add_f32 v[36:37], v[36:37], v[68:69]
	v_pk_add_f32 v[38:39], v[38:39], v[70:71]
	v_pk_add_f32 v[40:41], v[40:41], v[72:73]
	v_pk_add_f32 v[42:43], v[42:43], v[74:75]
	v_pk_add_f32 v[44:45], v[44:45], v[76:77]
	v_pk_add_f32 v[46:47], v[46:47], v[78:79]
	v_pk_add_f32 v[32:33], v[32:33], v[80:81]
	v_pk_add_f32 v[34:35], v[34:35], v[82:83]
	v_pk_add_f32 v[36:37], v[36:37], v[84:85]
	v_pk_add_f32 v[38:39], v[38:39], v[86:87]
	v_pk_add_f32 v[40:41], v[40:41], v[88:89]
	v_pk_add_f32 v[42:43], v[42:43], v[90:91]
	v_pk_add_f32 v[44:45], v[44:45], v[92:93]
	v_pk_add_f32 v[46:47], v[46:47], v[94:95]
	v_pk_add_f32 v[32:33], v[32:33], v[96:97]
	v_pk_add_f32 v[34:35], v[34:35], v[98:99]
	v_pk_add_f32 v[36:37], v[36:37], v[100:101]
	v_pk_add_f32 v[38:39], v[38:39], v[102:103]
	v_pk_add_f32 v[40:41], v[40:41], v[104:105]
	v_pk_add_f32 v[42:43], v[42:43], v[106:107]
	v_pk_add_f32 v[44:45], v[44:45], v[108:109]
	v_pk_add_f32 v[46:47], v[46:47], v[110:111]
	s_add_u32 s10, s26, 0x4000000
	s_addc_u32 s11, s27, 0
	global_store_dwordx4 v152, v[32:35], s[10:11]
	global_store_dwordx4 v152, v[36:39], s[10:11] offset:1024
	global_store_dwordx4 v152, v[40:43], s[10:11] offset:2048
	global_store_dwordx4 v152, v[44:47], s[10:11] offset:3072
	v_readlane_b32 s10, v255, 10
	v_readlane_b32 s11, v255, 11
	s_nop 1
	s_and_b64 vcc, exec, s[10:11]
	s_cbranch_vccz .Lp6b_noxb
	v_cvt_pk_bf16_f32 v28, v32, v33
	v_cvt_pk_bf16_f32 v29, v34, v35
	global_store_dwordx2 v[16:17], v[28:29], off offset:-1536
	v_cvt_pk_bf16_f32 v30, v36, v37
	v_cvt_pk_bf16_f32 v31, v38, v39
	global_store_dwordx2 v[16:17], v[30:31], off offset:-1024
	v_cvt_pk_bf16_f32 v28, v40, v41
	v_cvt_pk_bf16_f32 v29, v42, v43
	global_store_dwordx2 v[16:17], v[28:29], off offset:-512
	v_cvt_pk_bf16_f32 v30, v44, v45
	v_cvt_pk_bf16_f32 v31, v46, v47
	global_store_dwordx2 v[16:17], v[30:31], off offset:0
.Lp6b_noxb:
	v_mov_b32_e32 v0, v32
	v_mov_b32_e32 v1, v33
	v_mov_b32_e32 v2, v34
	v_mov_b32_e32 v3, v35
	v_mov_b32_e32 v4, v36
	v_mov_b32_e32 v5, v37
	v_mov_b32_e32 v6, v38
	v_mov_b32_e32 v7, v39
	v_mov_b32_e32 v8, v40
	v_mov_b32_e32 v9, v41
	v_mov_b32_e32 v10, v42
	v_mov_b32_e32 v11, v43
	v_mov_b32_e32 v12, v44
	v_mov_b32_e32 v13, v45
	v_mov_b32_e32 v14, v46
	v_mov_b32_e32 v15, v47
